# SwiGLU row-sum loads issued in the last K-loop iteration (after its last counted wait) so the epilogue does not wait for them; on top of 0x6000 split
# baseline (speedup 1.0000x reference)
.LBB0_476:
	ds_read_b128 v[142:145], v151
	ds_read_b128 v[156:159], v151 offset:1024
	ds_read_b128 v[160:163], v151 offset:2048
	ds_read_b128 v[164:167], v151 offset:3072
	ds_read_b128 v[168:171], v152
	ds_read_b128 v[172:175], v152 offset:1024
	ds_read_b128 v[176:179], v152 offset:2048
	ds_read_b128 v[180:183], v152 offset:3072
	s_add_u32 s2, s24, 0xfff00080
	s_addc_u32 s3, s25, -1
	s_cmp_eq_u32 s62, 60
	s_cselect_b32 s27, s15, s3
	s_cselect_b32 s26, s28, s2
	s_cselect_b32 s3, s13, s61
	s_cselect_b32 s2, s29, s33
	v_lshl_add_u64 v[146:147], s[24:25], 0, v[138:139]
	s_add_i32 m0, s23, 0xc000
	ds_read_b128 v[184:187], v153
	ds_read_b128 v[188:191], v153 offset:1024
	ds_read_b128 v[192:195], v153 offset:2048
	ds_read_b128 v[196:199], v153 offset:3072
	ds_read_b128 v[200:203], v153 offset:4096
	ds_read_b128 v[204:207], v153 offset:5120
	ds_read_b128 v[208:211], v153 offset:6144
	ds_read_b128 v[212:215], v153 offset:7168
	global_load_lds_dwordx4 v[146:147], off
	v_lshl_add_u64 v[146:147], s[24:25], 0, v[140:141]
	s_add_i32 m0, s23, 0xe000
	s_nop 0
	global_load_lds_dwordx4 v[146:147], off
	s_waitcnt vmcnt(8)
	s_waitcnt lgkmcnt(0)
	s_barrier
	s_setprio 1
	s_waitcnt lgkmcnt(0)
	v_mfma_f32_16x16x32_bf16 v[118:121], v[142:145], v[184:187], v[118:121]
	v_mfma_f32_16x16x32_bf16 v[114:117], v[160:163], v[184:187], v[114:117]
	v_mfma_f32_16x16x32_bf16 v[102:105], v[142:145], v[192:195], v[102:105]
	v_mfma_f32_16x16x32_bf16 v[98:101], v[160:163], v[192:195], v[98:101]
	v_mfma_f32_16x16x32_bf16 v[86:89], v[142:145], v[200:203], v[86:89]
	v_mfma_f32_16x16x32_bf16 v[82:85], v[160:163], v[200:203], v[82:85]
	v_mfma_f32_16x16x32_bf16 v[70:73], v[142:145], v[208:211], v[70:73]
	v_mfma_f32_16x16x32_bf16 v[66:69], v[160:163], v[208:211], v[66:69]
	v_mfma_f32_16x16x32_bf16 v[118:121], v[156:159], v[188:191], v[118:121]
	v_mfma_f32_16x16x32_bf16 v[114:117], v[164:167], v[188:191], v[114:117]
	v_mfma_f32_16x16x32_bf16 v[102:105], v[156:159], v[196:199], v[102:105]
	v_mfma_f32_16x16x32_bf16 v[98:101], v[164:167], v[196:199], v[98:101]
	v_mfma_f32_16x16x32_bf16 v[86:89], v[156:159], v[204:207], v[86:89]
	v_mfma_f32_16x16x32_bf16 v[82:85], v[164:167], v[204:207], v[82:85]
	v_mfma_f32_16x16x32_bf16 v[70:73], v[156:159], v[212:215], v[70:73]
	v_mfma_f32_16x16x32_bf16 v[66:69], v[164:167], v[212:215], v[66:69]
	s_setprio 0
	s_setprio 1
	v_mfma_f32_16x16x32_bf16 v[126:129], v[168:171], v[184:187], v[126:129]
	v_mfma_f32_16x16x32_bf16 v[122:125], v[176:179], v[184:187], v[122:125]
	v_mfma_f32_16x16x32_bf16 v[110:113], v[168:171], v[192:195], v[110:113]
	v_mfma_f32_16x16x32_bf16 v[106:109], v[176:179], v[192:195], v[106:109]
	v_mfma_f32_16x16x32_bf16 v[94:97], v[168:171], v[200:203], v[94:97]
	v_mfma_f32_16x16x32_bf16 v[90:93], v[176:179], v[200:203], v[90:93]
	v_mfma_f32_16x16x32_bf16 v[78:81], v[168:171], v[208:211], v[78:81]
	v_mfma_f32_16x16x32_bf16 v[74:77], v[176:179], v[208:211], v[74:77]
	v_mfma_f32_16x16x32_bf16 v[126:129], v[172:175], v[188:191], v[126:129]
	v_mfma_f32_16x16x32_bf16 v[122:125], v[180:183], v[188:191], v[122:125]
	v_mfma_f32_16x16x32_bf16 v[110:113], v[172:175], v[196:199], v[110:113]
	v_mfma_f32_16x16x32_bf16 v[106:109], v[180:183], v[196:199], v[106:109]
	v_mfma_f32_16x16x32_bf16 v[94:97], v[172:175], v[204:207], v[94:97]
	v_mfma_f32_16x16x32_bf16 v[90:93], v[180:183], v[204:207], v[90:93]
	v_mfma_f32_16x16x32_bf16 v[78:81], v[172:175], v[212:215], v[78:81]
	v_mfma_f32_16x16x32_bf16 v[74:77], v[180:183], v[212:215], v[74:77]
	s_setprio 0
	s_barrier
	s_add_i32 s63, s58, s45
	v_lshl_add_u64 v[146:147], s[2:3], 0, v[132:133]
	s_mov_b32 m0, s63
	ds_read_b128 v[184:187], v153 offset:16384
	ds_read_b128 v[188:191], v153 offset:17408
	ds_read_b128 v[192:195], v153 offset:18432
	ds_read_b128 v[196:199], v153 offset:19456
	ds_read_b128 v[200:203], v153 offset:20480
	ds_read_b128 v[204:207], v153 offset:21504
	ds_read_b128 v[208:211], v153 offset:22528
	ds_read_b128 v[212:215], v153 offset:23552
	global_load_lds_dwordx4 v[146:147], off
	s_add_i32 m0, s63, 0x2000
	s_add_u32 s64, s2, 0x100000
	v_lshl_add_u64 v[216:217], s[2:3], 0, v[136:137]
	s_addc_u32 s65, s3, 0
	s_add_i32 s63, s59, s45
	global_load_lds_dwordx4 v[216:217], off
	v_lshl_add_u64 v[218:219], s[64:65], 0, v[132:133]
	s_mov_b32 m0, s63
	v_lshl_add_u64 v[220:221], s[26:27], 0, v[134:135]
	global_load_lds_dwordx4 v[218:219], off
	v_lshl_add_u64 v[218:219], s[64:65], 0, v[136:137]
	s_add_i32 m0, s63, 0x2000
	s_nop 0
	global_load_lds_dwordx4 v[218:219], off
	v_lshl_add_u64 v[218:219], s[26:27], 0, v[130:131]
	s_mov_b32 m0, s23
	s_nop 0
	global_load_lds_dwordx4 v[218:219], off
	s_mov_b32 m0, s37
	s_nop 0
	global_load_lds_dwordx4 v[220:221], off
	s_waitcnt vmcnt(8)
	s_waitcnt lgkmcnt(0)
	s_barrier
	s_setprio 1
	s_waitcnt lgkmcnt(0)
	v_mfma_f32_16x16x32_bf16 v[54:57], v[142:145], v[184:187], v[54:57]
	v_mfma_f32_16x16x32_bf16 v[50:53], v[160:163], v[184:187], v[50:53]
	v_mfma_f32_16x16x32_bf16 v[38:41], v[142:145], v[192:195], v[38:41]
	v_mfma_f32_16x16x32_bf16 v[34:37], v[160:163], v[192:195], v[34:37]
	v_mfma_f32_16x16x32_bf16 v[22:25], v[142:145], v[200:203], v[22:25]
	v_mfma_f32_16x16x32_bf16 v[18:21], v[160:163], v[200:203], v[18:21]
	v_mfma_f32_16x16x32_bf16 v[6:9], v[142:145], v[208:211], v[6:9]
	v_mfma_f32_16x16x32_bf16 v[2:5], v[160:163], v[208:211], v[2:5]
	v_mfma_f32_16x16x32_bf16 v[54:57], v[156:159], v[188:191], v[54:57]
	v_mfma_f32_16x16x32_bf16 v[50:53], v[164:167], v[188:191], v[50:53]
	v_mfma_f32_16x16x32_bf16 v[38:41], v[156:159], v[196:199], v[38:41]
	v_mfma_f32_16x16x32_bf16 v[34:37], v[164:167], v[196:199], v[34:37]
	v_mfma_f32_16x16x32_bf16 v[22:25], v[156:159], v[204:207], v[22:25]
	v_mfma_f32_16x16x32_bf16 v[18:21], v[164:167], v[204:207], v[18:21]
	v_mfma_f32_16x16x32_bf16 v[6:9], v[156:159], v[212:215], v[6:9]
	v_mfma_f32_16x16x32_bf16 v[2:5], v[164:167], v[212:215], v[2:5]
	s_setprio 0
	s_setprio 1
	v_mfma_f32_16x16x32_bf16 v[62:65], v[168:171], v[184:187], v[62:65]
	v_mfma_f32_16x16x32_bf16 v[58:61], v[176:179], v[184:187], v[58:61]
	v_mfma_f32_16x16x32_bf16 v[46:49], v[168:171], v[192:195], v[46:49]
	v_mfma_f32_16x16x32_bf16 v[42:45], v[176:179], v[192:195], v[42:45]
	v_mfma_f32_16x16x32_bf16 v[30:33], v[168:171], v[200:203], v[30:33]
	v_mfma_f32_16x16x32_bf16 v[26:29], v[176:179], v[200:203], v[26:29]
	v_mfma_f32_16x16x32_bf16 v[14:17], v[168:171], v[208:211], v[14:17]
	v_mfma_f32_16x16x32_bf16 v[10:13], v[176:179], v[208:211], v[10:13]
	v_mfma_f32_16x16x32_bf16 v[62:65], v[172:175], v[188:191], v[62:65]
	v_mfma_f32_16x16x32_bf16 v[58:61], v[180:183], v[188:191], v[58:61]
	v_mfma_f32_16x16x32_bf16 v[46:49], v[172:175], v[196:199], v[46:49]
	v_mfma_f32_16x16x32_bf16 v[42:45], v[180:183], v[196:199], v[42:45]
	v_mfma_f32_16x16x32_bf16 v[30:33], v[172:175], v[204:207], v[30:33]
	v_mfma_f32_16x16x32_bf16 v[26:29], v[180:183], v[204:207], v[26:29]
	v_mfma_f32_16x16x32_bf16 v[14:17], v[172:175], v[212:215], v[14:17]
	v_mfma_f32_16x16x32_bf16 v[10:13], v[180:183], v[212:215], v[10:13]
	s_setprio 0
	s_barrier
	s_add_i32 s63, 0, 0x18000
	s_add_i32 s64, 0, 0x1c000
	v_add_u32_e32 v164, s63, v149
	v_add_u32_e32 v180, s64, v149
	ds_read_b128 v[142:145], v164
	ds_read_b128 v[156:159], v164 offset:1024
	ds_read_b128 v[160:163], v164 offset:2048
	ds_read_b128 v[164:167], v164 offset:3072
	ds_read_b128 v[168:171], v180
	ds_read_b128 v[172:175], v180 offset:1024
	ds_read_b128 v[176:179], v180 offset:2048
	ds_read_b128 v[180:183], v180 offset:3072
	s_add_u32 s26, s26, 0x100000
	s_addc_u32 s27, s27, 0
	s_mov_b32 m0, s46
	v_lshl_add_u64 v[222:223], s[26:27], 0, v[130:131]
	ds_read_b128 v[184:187], v153 offset:32768
	ds_read_b128 v[188:191], v153 offset:33792
	ds_read_b128 v[192:195], v153 offset:34816
	ds_read_b128 v[196:199], v153 offset:35840
	ds_read_b128 v[200:203], v153 offset:36864
	ds_read_b128 v[204:207], v153 offset:37888
	ds_read_b128 v[208:211], v153 offset:38912
	ds_read_b128 v[212:215], v153 offset:39936
	global_load_lds_dwordx4 v[222:223], off
	v_lshl_add_u64 v[222:223], s[26:27], 0, v[134:135]
	s_mov_b32 m0, s47
	s_nop 0
	global_load_lds_dwordx4 v[222:223], off
	s_waitcnt vmcnt(8)
	s_waitcnt lgkmcnt(0)
	s_barrier
	s_setprio 1
	s_waitcnt lgkmcnt(0)
	v_mfma_f32_16x16x32_bf16 v[118:121], v[142:145], v[184:187], v[118:121]
	v_mfma_f32_16x16x32_bf16 v[114:117], v[160:163], v[184:187], v[114:117]
	v_mfma_f32_16x16x32_bf16 v[102:105], v[142:145], v[192:195], v[102:105]
	v_mfma_f32_16x16x32_bf16 v[98:101], v[160:163], v[192:195], v[98:101]
	v_mfma_f32_16x16x32_bf16 v[86:89], v[142:145], v[200:203], v[86:89]
	v_mfma_f32_16x16x32_bf16 v[82:85], v[160:163], v[200:203], v[82:85]
	v_mfma_f32_16x16x32_bf16 v[70:73], v[142:145], v[208:211], v[70:73]
	v_mfma_f32_16x16x32_bf16 v[66:69], v[160:163], v[208:211], v[66:69]
	v_mfma_f32_16x16x32_bf16 v[118:121], v[156:159], v[188:191], v[118:121]
	v_mfma_f32_16x16x32_bf16 v[114:117], v[164:167], v[188:191], v[114:117]
	v_mfma_f32_16x16x32_bf16 v[102:105], v[156:159], v[196:199], v[102:105]
	v_mfma_f32_16x16x32_bf16 v[98:101], v[164:167], v[196:199], v[98:101]
	v_mfma_f32_16x16x32_bf16 v[86:89], v[156:159], v[204:207], v[86:89]
	v_mfma_f32_16x16x32_bf16 v[82:85], v[164:167], v[204:207], v[82:85]
	v_mfma_f32_16x16x32_bf16 v[70:73], v[156:159], v[212:215], v[70:73]
	v_mfma_f32_16x16x32_bf16 v[66:69], v[164:167], v[212:215], v[66:69]
	s_setprio 0
	s_setprio 1
	v_mfma_f32_16x16x32_bf16 v[126:129], v[168:171], v[184:187], v[126:129]
	v_mfma_f32_16x16x32_bf16 v[122:125], v[176:179], v[184:187], v[122:125]
	v_mfma_f32_16x16x32_bf16 v[110:113], v[168:171], v[192:195], v[110:113]
	v_mfma_f32_16x16x32_bf16 v[106:109], v[176:179], v[192:195], v[106:109]
	v_mfma_f32_16x16x32_bf16 v[94:97], v[168:171], v[200:203], v[94:97]
	v_mfma_f32_16x16x32_bf16 v[90:93], v[176:179], v[200:203], v[90:93]
	v_mfma_f32_16x16x32_bf16 v[78:81], v[168:171], v[208:211], v[78:81]
	v_mfma_f32_16x16x32_bf16 v[74:77], v[176:179], v[208:211], v[74:77]
	v_mfma_f32_16x16x32_bf16 v[126:129], v[172:175], v[188:191], v[126:129]
	v_mfma_f32_16x16x32_bf16 v[122:125], v[180:183], v[188:191], v[122:125]
	v_mfma_f32_16x16x32_bf16 v[110:113], v[172:175], v[196:199], v[110:113]
	v_mfma_f32_16x16x32_bf16 v[106:109], v[180:183], v[196:199], v[106:109]
	v_mfma_f32_16x16x32_bf16 v[94:97], v[172:175], v[204:207], v[94:97]
	v_mfma_f32_16x16x32_bf16 v[90:93], v[180:183], v[204:207], v[90:93]
	v_mfma_f32_16x16x32_bf16 v[78:81], v[172:175], v[212:215], v[78:81]
	v_mfma_f32_16x16x32_bf16 v[74:77], v[180:183], v[212:215], v[74:77]
	s_setprio 0
	s_barrier
	s_add_i32 s26, s63, s45
	v_lshl_add_u64 v[146:147], v[146:147], 0, s[8:9]
	s_mov_b32 m0, s26
	ds_read_b128 v[184:187], v153 offset:49152
	ds_read_b128 v[188:191], v153 offset:50176
	ds_read_b128 v[192:195], v153 offset:51200
	ds_read_b128 v[196:199], v153 offset:52224
	ds_read_b128 v[200:203], v153 offset:53248
	ds_read_b128 v[204:207], v153 offset:54272
	ds_read_b128 v[208:211], v153 offset:55296
	ds_read_b128 v[212:215], v153 offset:56320
	global_load_lds_dwordx4 v[146:147], off
	s_add_i32 m0, s26, 0x2000
	s_add_u32 s2, s2, 0x100080
	v_lshl_add_u64 v[146:147], v[216:217], 0, s[8:9]
	s_addc_u32 s3, s3, 0
	s_add_i32 s26, s64, s45
	global_load_lds_dwordx4 v[146:147], off
	v_lshl_add_u64 v[146:147], s[2:3], 0, v[132:133]
	s_mov_b32 m0, s26
	s_nop 0
	global_load_lds_dwordx4 v[146:147], off
	v_lshl_add_u64 v[146:147], s[2:3], 0, v[136:137]
	s_add_i32 m0, s26, 0x2000
	s_nop 0
	global_load_lds_dwordx4 v[146:147], off
	v_lshl_add_u64 v[146:147], v[218:219], 0, s[8:9]
	s_mov_b32 m0, s49
	s_nop 0
	global_load_lds_dwordx4 v[146:147], off
	v_lshl_add_u64 v[146:147], v[220:221], 0, s[8:9]
	s_mov_b32 m0, s52
	s_nop 0
	global_load_lds_dwordx4 v[146:147], off
	s_waitcnt vmcnt(8)
	s_cmp_lg_u32 s62, 60
	s_cbranch_scc1 .Lssq_skip_0
	v_lshl_add_u32 v146, s36, 8, v148
	v_ashrrev_i32_e32 v147, 31, v146
	v_lshl_add_u64 v[146:147], v[146:147], 2, s[4:5]
	global_load_dword v241, v[146:147], off
	global_load_dword v242, v[146:147], off offset:64
	global_load_dword v243, v[146:147], off offset:128
	global_load_dword v244, v[146:147], off offset:192
	global_load_dword v245, v[146:147], off offset:512
	global_load_dword v246, v[146:147], off offset:576
	global_load_dword v247, v[146:147], off offset:640
	global_load_dword v248, v[146:147], off offset:704
.Lssq_skip_0:
	s_waitcnt lgkmcnt(0)
	s_barrier
	s_setprio 1
	s_waitcnt lgkmcnt(0)
	v_mfma_f32_16x16x32_bf16 v[54:57], v[142:145], v[184:187], v[54:57]
	v_mfma_f32_16x16x32_bf16 v[50:53], v[160:163], v[184:187], v[50:53]
	v_mfma_f32_16x16x32_bf16 v[38:41], v[142:145], v[192:195], v[38:41]
	v_mfma_f32_16x16x32_bf16 v[34:37], v[160:163], v[192:195], v[34:37]
	v_mfma_f32_16x16x32_bf16 v[22:25], v[142:145], v[200:203], v[22:25]
	v_mfma_f32_16x16x32_bf16 v[18:21], v[160:163], v[200:203], v[18:21]
	v_mfma_f32_16x16x32_bf16 v[6:9], v[142:145], v[208:211], v[6:9]
	v_mfma_f32_16x16x32_bf16 v[2:5], v[160:163], v[208:211], v[2:5]
	v_mfma_f32_16x16x32_bf16 v[54:57], v[156:159], v[188:191], v[54:57]
	v_mfma_f32_16x16x32_bf16 v[50:53], v[164:167], v[188:191], v[50:53]
	v_mfma_f32_16x16x32_bf16 v[38:41], v[156:159], v[196:199], v[38:41]
	v_mfma_f32_16x16x32_bf16 v[34:37], v[164:167], v[196:199], v[34:37]
	v_mfma_f32_16x16x32_bf16 v[22:25], v[156:159], v[204:207], v[22:25]
	v_mfma_f32_16x16x32_bf16 v[18:21], v[164:167], v[204:207], v[18:21]
	v_mfma_f32_16x16x32_bf16 v[6:9], v[156:159], v[212:215], v[6:9]
	v_mfma_f32_16x16x32_bf16 v[2:5], v[164:167], v[212:215], v[2:5]
	s_setprio 0
	s_setprio 1
	v_mfma_f32_16x16x32_bf16 v[62:65], v[168:171], v[184:187], v[62:65]
	v_mfma_f32_16x16x32_bf16 v[58:61], v[176:179], v[184:187], v[58:61]
	v_mfma_f32_16x16x32_bf16 v[46:49], v[168:171], v[192:195], v[46:49]
	v_mfma_f32_16x16x32_bf16 v[42:45], v[176:179], v[192:195], v[42:45]
	v_mfma_f32_16x16x32_bf16 v[30:33], v[168:171], v[200:203], v[30:33]
	v_mfma_f32_16x16x32_bf16 v[26:29], v[176:179], v[200:203], v[26:29]
	v_mfma_f32_16x16x32_bf16 v[14:17], v[168:171], v[208:211], v[14:17]
	v_mfma_f32_16x16x32_bf16 v[10:13], v[176:179], v[208:211], v[10:13]
	v_mfma_f32_16x16x32_bf16 v[62:65], v[172:175], v[188:191], v[62:65]
	v_mfma_f32_16x16x32_bf16 v[58:61], v[180:183], v[188:191], v[58:61]
	v_mfma_f32_16x16x32_bf16 v[46:49], v[172:175], v[196:199], v[46:49]
	v_mfma_f32_16x16x32_bf16 v[42:45], v[180:183], v[196:199], v[42:45]
	v_mfma_f32_16x16x32_bf16 v[30:33], v[172:175], v[204:207], v[30:33]
	v_mfma_f32_16x16x32_bf16 v[26:29], v[180:183], v[204:207], v[26:29]
	v_mfma_f32_16x16x32_bf16 v[14:17], v[172:175], v[212:215], v[14:17]
	v_mfma_f32_16x16x32_bf16 v[10:13], v[180:183], v[212:215], v[10:13]
	s_setprio 0
	s_barrier
	s_add_i32 s62, s62, 2
	s_add_u32 s24, s24, 0x100
	s_addc_u32 s25, s25, 0
	s_add_u32 s33, s33, 0x100
	s_addc_u32 s61, s61, 0
	s_cmp_gt_u32 s62, 61
	s_cbranch_scc0 .LBB0_476
	s_and_b64 vcc, exec, s[10:11]
	s_cbranch_vccz .LBB0_479
	s_barrier
.LBB0_479:
	v_lshl_add_u32 v142, s36, 8, v148
	v_ashrrev_i32_e32 v143, 31, v142
	v_lshl_add_u64 v[146:147], v[142:143], 2, s[4:5]
	v_lshl_or_b32 v144, s22, 7, v150
	v_ashrrev_i32_e32 v145, 31, v144
	v_mov_b32_e32 v254, 1.0
	v_lshl_add_u64 v[144:145], v[144:145], 1, s[6:7]
	s_andn2_b64 vcc, exec, s[38:39]
	v_mad_i64_i32 v[146:147], s[2:3], v142, s60, v[144:145]
	s_waitcnt vmcnt(7)
	v_fmamk_f32 v251, v241, 0x39800000, v155
	v_rsq_f32_e32 v251, v251
	v_pk_mul_f32 v[126:127], v[118:119], v[126:127]
	v_pk_mul_f32 v[128:129], v[120:121], v[128:129]
	v_pk_mul_f32 v[122:123], v[114:115], v[122:123]
	v_pk_mul_f32 v[124:125], v[116:117], v[124:125]
	v_mul_f32_e32 v250, 0xbfb8aa3b, v251
	v_mul_f32_e32 v252, v251, v251
	v_pk_mul_f32 v[118:119], v[118:119], v[250:251] op_sel_hi:[1,0]
	v_pk_mul_f32 v[120:121], v[120:121], v[250:251] op_sel_hi:[1,0]
	v_pk_mul_f32 v[114:115], v[114:115], v[250:251] op_sel_hi:[1,0]
	v_pk_mul_f32 v[116:117], v[116:117], v[250:251] op_sel_hi:[1,0]
	v_exp_f32_e32 v118, v118
	v_exp_f32_e32 v119, v119
	v_exp_f32_e32 v120, v120
	v_exp_f32_e32 v121, v121
	v_exp_f32_e32 v114, v114
	v_exp_f32_e32 v115, v115
	v_exp_f32_e32 v116, v116
	v_exp_f32_e32 v117, v117
	v_pk_add_f32 v[118:119], v[118:119], v[254:255] op_sel_hi:[1,0]
	v_pk_add_f32 v[120:121], v[120:121], v[254:255] op_sel_hi:[1,0]
	v_pk_add_f32 v[114:115], v[114:115], v[254:255] op_sel_hi:[1,0]
	v_pk_add_f32 v[116:117], v[116:117], v[254:255] op_sel_hi:[1,0]
	v_rcp_f32_e32 v118, v118
	v_rcp_f32_e32 v119, v119
	v_rcp_f32_e32 v120, v120
	v_rcp_f32_e32 v121, v121
	v_rcp_f32_e32 v114, v114
	v_rcp_f32_e32 v115, v115
	v_rcp_f32_e32 v116, v116
	v_rcp_f32_e32 v117, v117
	v_pk_mul_f32 v[118:119], v[118:119], v[252:253] op_sel_hi:[1,0]
	v_pk_mul_f32 v[120:121], v[120:121], v[252:253] op_sel_hi:[1,0]
	v_pk_mul_f32 v[114:115], v[114:115], v[252:253] op_sel_hi:[1,0]
	v_pk_mul_f32 v[116:117], v[116:117], v[252:253] op_sel_hi:[1,0]
	v_pk_mul_f32 v[118:119], v[126:127], v[118:119]
	v_pk_mul_f32 v[120:121], v[128:129], v[120:121]
	v_pk_mul_f32 v[114:115], v[122:123], v[114:115]
	v_pk_mul_f32 v[116:117], v[124:125], v[116:117]
	v_cvt_pk_bf16_f32 v122, v118, v119
	v_cvt_pk_bf16_f32 v123, v120, v121
	v_cvt_pk_bf16_f32 v124, v114, v115
	v_cvt_pk_bf16_f32 v125, v116, v117
	global_store_dwordx4 v[146:147], v[122:125], off
	v_add_u32_e32 v253, 16, v142
	v_mad_i64_i32 v[146:147], s[2:3], v253, s60, v[144:145]
	s_waitcnt vmcnt(6)
	v_fmamk_f32 v251, v242, 0x39800000, v155
	v_rsq_f32_e32 v251, v251
	v_pk_mul_f32 v[110:111], v[102:103], v[110:111]
	v_pk_mul_f32 v[112:113], v[104:105], v[112:113]
	v_pk_mul_f32 v[106:107], v[98:99], v[106:107]
	v_pk_mul_f32 v[108:109], v[100:101], v[108:109]
	v_mul_f32_e32 v250, 0xbfb8aa3b, v251
	v_mul_f32_e32 v252, v251, v251
	v_pk_mul_f32 v[102:103], v[102:103], v[250:251] op_sel_hi:[1,0]
	v_pk_mul_f32 v[104:105], v[104:105], v[250:251] op_sel_hi:[1,0]
	v_pk_mul_f32 v[98:99], v[98:99], v[250:251] op_sel_hi:[1,0]
	v_pk_mul_f32 v[100:101], v[100:101], v[250:251] op_sel_hi:[1,0]
	v_exp_f32_e32 v102, v102
	v_exp_f32_e32 v103, v103
	v_exp_f32_e32 v104, v104
	v_exp_f32_e32 v105, v105
	v_exp_f32_e32 v98, v98
	v_exp_f32_e32 v99, v99
	v_exp_f32_e32 v100, v100
	v_exp_f32_e32 v101, v101
	v_pk_add_f32 v[102:103], v[102:103], v[254:255] op_sel_hi:[1,0]
	v_pk_add_f32 v[104:105], v[104:105], v[254:255] op_sel_hi:[1,0]
	v_pk_add_f32 v[98:99], v[98:99], v[254:255] op_sel_hi:[1,0]
	v_pk_add_f32 v[100:101], v[100:101], v[254:255] op_sel_hi:[1,0]
	v_rcp_f32_e32 v102, v102
	v_rcp_f32_e32 v103, v103
	v_rcp_f32_e32 v104, v104
	v_rcp_f32_e32 v105, v105
	v_rcp_f32_e32 v98, v98
	v_rcp_f32_e32 v99, v99
	v_rcp_f32_e32 v100, v100
	v_rcp_f32_e32 v101, v101
	v_pk_mul_f32 v[102:103], v[102:103], v[252:253] op_sel_hi:[1,0]
	v_pk_mul_f32 v[104:105], v[104:105], v[252:253] op_sel_hi:[1,0]
	v_pk_mul_f32 v[98:99], v[98:99], v[252:253] op_sel_hi:[1,0]
	v_pk_mul_f32 v[100:101], v[100:101], v[252:253] op_sel_hi:[1,0]
	v_pk_mul_f32 v[102:103], v[110:111], v[102:103]
	v_pk_mul_f32 v[104:105], v[112:113], v[104:105]
	v_pk_mul_f32 v[98:99], v[106:107], v[98:99]
	v_pk_mul_f32 v[100:101], v[108:109], v[100:101]
	v_cvt_pk_bf16_f32 v106, v102, v103
	v_cvt_pk_bf16_f32 v107, v104, v105
	v_cvt_pk_bf16_f32 v108, v98, v99
	v_cvt_pk_bf16_f32 v109, v100, v101
	global_store_dwordx4 v[146:147], v[106:109], off
	v_add_u32_e32 v253, 32, v142
	v_mad_i64_i32 v[146:147], s[2:3], v253, s60, v[144:145]
	s_waitcnt vmcnt(5)
	v_fmamk_f32 v251, v243, 0x39800000, v155
	v_rsq_f32_e32 v251, v251
	v_pk_mul_f32 v[94:95], v[86:87], v[94:95]
	v_pk_mul_f32 v[96:97], v[88:89], v[96:97]
	v_pk_mul_f32 v[90:91], v[82:83], v[90:91]
	v_pk_mul_f32 v[92:93], v[84:85], v[92:93]
	v_mul_f32_e32 v250, 0xbfb8aa3b, v251
	v_mul_f32_e32 v252, v251, v251
	v_pk_mul_f32 v[86:87], v[86:87], v[250:251] op_sel_hi:[1,0]
	v_pk_mul_f32 v[88:89], v[88:89], v[250:251] op_sel_hi:[1,0]
	v_pk_mul_f32 v[82:83], v[82:83], v[250:251] op_sel_hi:[1,0]
	v_pk_mul_f32 v[84:85], v[84:85], v[250:251] op_sel_hi:[1,0]
	v_exp_f32_e32 v86, v86
	v_exp_f32_e32 v87, v87
	v_exp_f32_e32 v88, v88
	v_exp_f32_e32 v89, v89
	v_exp_f32_e32 v82, v82
	v_exp_f32_e32 v83, v83
	v_exp_f32_e32 v84, v84
	v_exp_f32_e32 v85, v85
	v_pk_add_f32 v[86:87], v[86:87], v[254:255] op_sel_hi:[1,0]
	v_pk_add_f32 v[88:89], v[88:89], v[254:255] op_sel_hi:[1,0]
	v_pk_add_f32 v[82:83], v[82:83], v[254:255] op_sel_hi:[1,0]
	v_pk_add_f32 v[84:85], v[84:85], v[254:255] op_sel_hi:[1,0]
	v_rcp_f32_e32 v86, v86
	v_rcp_f32_e32 v87, v87
	v_rcp_f32_e32 v88, v88
	v_rcp_f32_e32 v89, v89
	v_rcp_f32_e32 v82, v82
	v_rcp_f32_e32 v83, v83
	v_rcp_f32_e32 v84, v84
	v_rcp_f32_e32 v85, v85
	v_pk_mul_f32 v[86:87], v[86:87], v[252:253] op_sel_hi:[1,0]
	v_pk_mul_f32 v[88:89], v[88:89], v[252:253] op_sel_hi:[1,0]
	v_pk_mul_f32 v[82:83], v[82:83], v[252:253] op_sel_hi:[1,0]
	v_pk_mul_f32 v[84:85], v[84:85], v[252:253] op_sel_hi:[1,0]
	v_pk_mul_f32 v[86:87], v[94:95], v[86:87]
	v_pk_mul_f32 v[88:89], v[96:97], v[88:89]
	v_pk_mul_f32 v[82:83], v[90:91], v[82:83]
	v_pk_mul_f32 v[84:85], v[92:93], v[84:85]
	v_cvt_pk_bf16_f32 v90, v86, v87
	v_cvt_pk_bf16_f32 v91, v88, v89
	v_cvt_pk_bf16_f32 v92, v82, v83
	v_cvt_pk_bf16_f32 v93, v84, v85
	global_store_dwordx4 v[146:147], v[90:93], off
	v_add_u32_e32 v253, 48, v142
	v_mad_i64_i32 v[146:147], s[2:3], v253, s60, v[144:145]
	s_waitcnt vmcnt(4)
	v_fmamk_f32 v251, v244, 0x39800000, v155
	v_rsq_f32_e32 v251, v251
	v_pk_mul_f32 v[78:79], v[70:71], v[78:79]
	v_pk_mul_f32 v[80:81], v[72:73], v[80:81]
	v_pk_mul_f32 v[74:75], v[66:67], v[74:75]
	v_pk_mul_f32 v[76:77], v[68:69], v[76:77]
	v_mul_f32_e32 v250, 0xbfb8aa3b, v251
	v_mul_f32_e32 v252, v251, v251
	v_pk_mul_f32 v[70:71], v[70:71], v[250:251] op_sel_hi:[1,0]
	v_pk_mul_f32 v[72:73], v[72:73], v[250:251] op_sel_hi:[1,0]
	v_pk_mul_f32 v[66:67], v[66:67], v[250:251] op_sel_hi:[1,0]
	v_pk_mul_f32 v[68:69], v[68:69], v[250:251] op_sel_hi:[1,0]
	v_exp_f32_e32 v70, v70
	v_exp_f32_e32 v71, v71
	v_exp_f32_e32 v72, v72
	v_exp_f32_e32 v73, v73
	v_exp_f32_e32 v66, v66
	v_exp_f32_e32 v67, v67
	v_exp_f32_e32 v68, v68
	v_exp_f32_e32 v69, v69
	v_pk_add_f32 v[70:71], v[70:71], v[254:255] op_sel_hi:[1,0]
	v_pk_add_f32 v[72:73], v[72:73], v[254:255] op_sel_hi:[1,0]
	v_pk_add_f32 v[66:67], v[66:67], v[254:255] op_sel_hi:[1,0]
	v_pk_add_f32 v[68:69], v[68:69], v[254:255] op_sel_hi:[1,0]
	v_rcp_f32_e32 v70, v70
	v_rcp_f32_e32 v71, v71
	v_rcp_f32_e32 v72, v72
	v_rcp_f32_e32 v73, v73
	v_rcp_f32_e32 v66, v66
	v_rcp_f32_e32 v67, v67
	v_rcp_f32_e32 v68, v68
	v_rcp_f32_e32 v69, v69
	v_pk_mul_f32 v[70:71], v[70:71], v[252:253] op_sel_hi:[1,0]
	v_pk_mul_f32 v[72:73], v[72:73], v[252:253] op_sel_hi:[1,0]
	v_pk_mul_f32 v[66:67], v[66:67], v[252:253] op_sel_hi:[1,0]
	v_pk_mul_f32 v[68:69], v[68:69], v[252:253] op_sel_hi:[1,0]
	v_pk_mul_f32 v[70:71], v[78:79], v[70:71]
	v_pk_mul_f32 v[72:73], v[80:81], v[72:73]
	v_pk_mul_f32 v[66:67], v[74:75], v[66:67]
	v_pk_mul_f32 v[68:69], v[76:77], v[68:69]
	v_cvt_pk_bf16_f32 v74, v70, v71
	v_cvt_pk_bf16_f32 v75, v72, v73
	v_cvt_pk_bf16_f32 v76, v66, v67
	v_cvt_pk_bf16_f32 v77, v68, v69
	global_store_dwordx4 v[146:147], v[74:77], off
	v_add_u32_e32 v253, 128, v142
	v_mad_i64_i32 v[146:147], s[2:3], v253, s60, v[144:145]
	s_waitcnt vmcnt(3)
	v_fmamk_f32 v251, v245, 0x39800000, v155
	v_rsq_f32_e32 v251, v251
	v_pk_mul_f32 v[62:63], v[54:55], v[62:63]
	v_pk_mul_f32 v[64:65], v[56:57], v[64:65]
	v_pk_mul_f32 v[58:59], v[50:51], v[58:59]
	v_pk_mul_f32 v[60:61], v[52:53], v[60:61]
	v_mul_f32_e32 v250, 0xbfb8aa3b, v251
	v_mul_f32_e32 v252, v251, v251
	v_pk_mul_f32 v[54:55], v[54:55], v[250:251] op_sel_hi:[1,0]
	v_pk_mul_f32 v[56:57], v[56:57], v[250:251] op_sel_hi:[1,0]
	v_pk_mul_f32 v[50:51], v[50:51], v[250:251] op_sel_hi:[1,0]
	v_pk_mul_f32 v[52:53], v[52:53], v[250:251] op_sel_hi:[1,0]
	v_exp_f32_e32 v54, v54
	v_exp_f32_e32 v55, v55
	v_exp_f32_e32 v56, v56
	v_exp_f32_e32 v57, v57
	v_exp_f32_e32 v50, v50
	v_exp_f32_e32 v51, v51
	v_exp_f32_e32 v52, v52
	v_exp_f32_e32 v53, v53
	v_pk_add_f32 v[54:55], v[54:55], v[254:255] op_sel_hi:[1,0]
	v_pk_add_f32 v[56:57], v[56:57], v[254:255] op_sel_hi:[1,0]
	v_pk_add_f32 v[50:51], v[50:51], v[254:255] op_sel_hi:[1,0]
	v_pk_add_f32 v[52:53], v[52:53], v[254:255] op_sel_hi:[1,0]
	v_rcp_f32_e32 v54, v54
	v_rcp_f32_e32 v55, v55
	v_rcp_f32_e32 v56, v56
	v_rcp_f32_e32 v57, v57
	v_rcp_f32_e32 v50, v50
	v_rcp_f32_e32 v51, v51
	v_rcp_f32_e32 v52, v52
	v_rcp_f32_e32 v53, v53
	v_pk_mul_f32 v[54:55], v[54:55], v[252:253] op_sel_hi:[1,0]
	v_pk_mul_f32 v[56:57], v[56:57], v[252:253] op_sel_hi:[1,0]
	v_pk_mul_f32 v[50:51], v[50:51], v[252:253] op_sel_hi:[1,0]
	v_pk_mul_f32 v[52:53], v[52:53], v[252:253] op_sel_hi:[1,0]
	v_pk_mul_f32 v[54:55], v[62:63], v[54:55]
	v_pk_mul_f32 v[56:57], v[64:65], v[56:57]
	v_pk_mul_f32 v[50:51], v[58:59], v[50:51]
	v_pk_mul_f32 v[52:53], v[60:61], v[52:53]
	v_cvt_pk_bf16_f32 v58, v54, v55
	v_cvt_pk_bf16_f32 v59, v56, v57
	v_cvt_pk_bf16_f32 v60, v50, v51
	v_cvt_pk_bf16_f32 v61, v52, v53
	global_store_dwordx4 v[146:147], v[58:61], off
	v_add_u32_e32 v253, 144, v142
	v_mad_i64_i32 v[146:147], s[2:3], v253, s60, v[144:145]
	s_waitcnt vmcnt(2)
	v_fmamk_f32 v251, v246, 0x39800000, v155
	v_rsq_f32_e32 v251, v251
	v_pk_mul_f32 v[46:47], v[38:39], v[46:47]
	v_pk_mul_f32 v[48:49], v[40:41], v[48:49]
	v_pk_mul_f32 v[42:43], v[34:35], v[42:43]
	v_pk_mul_f32 v[44:45], v[36:37], v[44:45]
	v_mul_f32_e32 v250, 0xbfb8aa3b, v251
	v_mul_f32_e32 v252, v251, v251
	v_pk_mul_f32 v[38:39], v[38:39], v[250:251] op_sel_hi:[1,0]
	v_pk_mul_f32 v[40:41], v[40:41], v[250:251] op_sel_hi:[1,0]
	v_pk_mul_f32 v[34:35], v[34:35], v[250:251] op_sel_hi:[1,0]
	v_pk_mul_f32 v[36:37], v[36:37], v[250:251] op_sel_hi:[1,0]
	v_exp_f32_e32 v38, v38
	v_exp_f32_e32 v39, v39
	v_exp_f32_e32 v40, v40
	v_exp_f32_e32 v41, v41
	v_exp_f32_e32 v34, v34
	v_exp_f32_e32 v35, v35
	v_exp_f32_e32 v36, v36
	v_exp_f32_e32 v37, v37
	v_pk_add_f32 v[38:39], v[38:39], v[254:255] op_sel_hi:[1,0]
	v_pk_add_f32 v[40:41], v[40:41], v[254:255] op_sel_hi:[1,0]
	v_pk_add_f32 v[34:35], v[34:35], v[254:255] op_sel_hi:[1,0]
	v_pk_add_f32 v[36:37], v[36:37], v[254:255] op_sel_hi:[1,0]
	v_rcp_f32_e32 v38, v38
	v_rcp_f32_e32 v39, v39
	v_rcp_f32_e32 v40, v40
	v_rcp_f32_e32 v41, v41
	v_rcp_f32_e32 v34, v34
	v_rcp_f32_e32 v35, v35
	v_rcp_f32_e32 v36, v36
	v_rcp_f32_e32 v37, v37
	v_pk_mul_f32 v[38:39], v[38:39], v[252:253] op_sel_hi:[1,0]
	v_pk_mul_f32 v[40:41], v[40:41], v[252:253] op_sel_hi:[1,0]
	v_pk_mul_f32 v[34:35], v[34:35], v[252:253] op_sel_hi:[1,0]
	v_pk_mul_f32 v[36:37], v[36:37], v[252:253] op_sel_hi:[1,0]
	v_pk_mul_f32 v[38:39], v[46:47], v[38:39]
	v_pk_mul_f32 v[40:41], v[48:49], v[40:41]
	v_pk_mul_f32 v[34:35], v[42:43], v[34:35]
	v_pk_mul_f32 v[36:37], v[44:45], v[36:37]
	v_cvt_pk_bf16_f32 v42, v38, v39
	v_cvt_pk_bf16_f32 v43, v40, v41
	v_cvt_pk_bf16_f32 v44, v34, v35
	v_cvt_pk_bf16_f32 v45, v36, v37
	global_store_dwordx4 v[146:147], v[42:45], off
	v_add_u32_e32 v253, 160, v142
	v_mad_i64_i32 v[146:147], s[2:3], v253, s60, v[144:145]
	s_waitcnt vmcnt(1)
	v_fmamk_f32 v251, v247, 0x39800000, v155
	v_rsq_f32_e32 v251, v251
	v_pk_mul_f32 v[30:31], v[22:23], v[30:31]
	v_pk_mul_f32 v[32:33], v[24:25], v[32:33]
	v_pk_mul_f32 v[26:27], v[18:19], v[26:27]
	v_pk_mul_f32 v[28:29], v[20:21], v[28:29]
	v_mul_f32_e32 v250, 0xbfb8aa3b, v251
	v_mul_f32_e32 v252, v251, v251
	v_pk_mul_f32 v[22:23], v[22:23], v[250:251] op_sel_hi:[1,0]
	v_pk_mul_f32 v[24:25], v[24:25], v[250:251] op_sel_hi:[1,0]
	v_pk_mul_f32 v[18:19], v[18:19], v[250:251] op_sel_hi:[1,0]
	v_pk_mul_f32 v[20:21], v[20:21], v[250:251] op_sel_hi:[1,0]
	v_exp_f32_e32 v22, v22
	v_exp_f32_e32 v23, v23
	v_exp_f32_e32 v24, v24
	v_exp_f32_e32 v25, v25
	v_exp_f32_e32 v18, v18
	v_exp_f32_e32 v19, v19
	v_exp_f32_e32 v20, v20
	v_exp_f32_e32 v21, v21
	v_pk_add_f32 v[22:23], v[22:23], v[254:255] op_sel_hi:[1,0]
	v_pk_add_f32 v[24:25], v[24:25], v[254:255] op_sel_hi:[1,0]
	v_pk_add_f32 v[18:19], v[18:19], v[254:255] op_sel_hi:[1,0]
	v_pk_add_f32 v[20:21], v[20:21], v[254:255] op_sel_hi:[1,0]
	v_rcp_f32_e32 v22, v22
	v_rcp_f32_e32 v23, v23
	v_rcp_f32_e32 v24, v24
	v_rcp_f32_e32 v25, v25
	v_rcp_f32_e32 v18, v18
	v_rcp_f32_e32 v19, v19
	v_rcp_f32_e32 v20, v20
	v_rcp_f32_e32 v21, v21
	v_pk_mul_f32 v[22:23], v[22:23], v[252:253] op_sel_hi:[1,0]
	v_pk_mul_f32 v[24:25], v[24:25], v[252:253] op_sel_hi:[1,0]
	v_pk_mul_f32 v[18:19], v[18:19], v[252:253] op_sel_hi:[1,0]
	v_pk_mul_f32 v[20:21], v[20:21], v[252:253] op_sel_hi:[1,0]
	v_pk_mul_f32 v[22:23], v[30:31], v[22:23]
	v_pk_mul_f32 v[24:25], v[32:33], v[24:25]
	v_pk_mul_f32 v[18:19], v[26:27], v[18:19]
	v_pk_mul_f32 v[20:21], v[28:29], v[20:21]
	v_cvt_pk_bf16_f32 v26, v22, v23
	v_cvt_pk_bf16_f32 v27, v24, v25
	v_cvt_pk_bf16_f32 v28, v18, v19
	v_cvt_pk_bf16_f32 v29, v20, v21
	global_store_dwordx4 v[146:147], v[26:29], off
	v_add_u32_e32 v253, 176, v142
	v_mad_i64_i32 v[146:147], s[2:3], v253, s60, v[144:145]
	s_mov_b64 s[2:3], -1
	s_waitcnt vmcnt(0)
	v_fmamk_f32 v251, v248, 0x39800000, v155
	v_rsq_f32_e32 v251, v251
	v_pk_mul_f32 v[14:15], v[6:7], v[14:15]
	v_pk_mul_f32 v[16:17], v[8:9], v[16:17]
	v_pk_mul_f32 v[10:11], v[2:3], v[10:11]
	v_pk_mul_f32 v[12:13], v[4:5], v[12:13]
	v_mul_f32_e32 v250, 0xbfb8aa3b, v251
	v_mul_f32_e32 v252, v251, v251
	v_pk_mul_f32 v[6:7], v[6:7], v[250:251] op_sel_hi:[1,0]
	v_pk_mul_f32 v[8:9], v[8:9], v[250:251] op_sel_hi:[1,0]
	v_pk_mul_f32 v[2:3], v[2:3], v[250:251] op_sel_hi:[1,0]
	v_pk_mul_f32 v[4:5], v[4:5], v[250:251] op_sel_hi:[1,0]
	v_exp_f32_e32 v6, v6
	v_exp_f32_e32 v7, v7
	v_exp_f32_e32 v8, v8
	v_exp_f32_e32 v9, v9
	v_exp_f32_e32 v2, v2
	v_exp_f32_e32 v3, v3
	v_exp_f32_e32 v4, v4
	v_exp_f32_e32 v5, v5
	v_pk_add_f32 v[6:7], v[6:7], v[254:255] op_sel_hi:[1,0]
	v_pk_add_f32 v[8:9], v[8:9], v[254:255] op_sel_hi:[1,0]
	v_pk_add_f32 v[2:3], v[2:3], v[254:255] op_sel_hi:[1,0]
	v_pk_add_f32 v[4:5], v[4:5], v[254:255] op_sel_hi:[1,0]
	v_rcp_f32_e32 v6, v6
	v_rcp_f32_e32 v7, v7
	v_rcp_f32_e32 v8, v8
	v_rcp_f32_e32 v9, v9
	v_rcp_f32_e32 v2, v2
	v_rcp_f32_e32 v3, v3
	v_rcp_f32_e32 v4, v4
	v_rcp_f32_e32 v5, v5
	v_pk_mul_f32 v[6:7], v[6:7], v[252:253] op_sel_hi:[1,0]
	v_pk_mul_f32 v[8:9], v[8:9], v[252:253] op_sel_hi:[1,0]
	v_pk_mul_f32 v[2:3], v[2:3], v[252:253] op_sel_hi:[1,0]
	v_pk_mul_f32 v[4:5], v[4:5], v[252:253] op_sel_hi:[1,0]
	v_pk_mul_f32 v[6:7], v[14:15], v[6:7]
	v_pk_mul_f32 v[8:9], v[16:17], v[8:9]
	v_pk_mul_f32 v[2:3], v[10:11], v[2:3]
	v_pk_mul_f32 v[4:5], v[12:13], v[4:5]
	v_cvt_pk_bf16_f32 v10, v6, v7
	v_cvt_pk_bf16_f32 v11, v8, v9
	v_cvt_pk_bf16_f32 v12, v2, v3
	v_cvt_pk_bf16_f32 v13, v4, v5
	global_store_dwordx4 v[146:147], v[10:13], off
	s_cbranch_vccnz .LBB0_401
	s_andn2_b64 vcc, exec, s[0:1]
	s_cbranch_vccnz .LBB0_400
	s_barrier
	s_branch .LBB0_400

.LBB0_1333:
	ds_read_b128 v[142:145], v159
	ds_read_b128 v[164:167], v159 offset:1024
	ds_read_b128 v[168:171], v159 offset:2048
	ds_read_b128 v[172:175], v159 offset:3072
	ds_read_b128 v[176:179], v160
	ds_read_b128 v[180:183], v160 offset:1024
	ds_read_b128 v[192:195], v160 offset:2048
	ds_read_b128 v[196:199], v160 offset:3072
	s_add_u32 s2, s24, 0xfff00080
	s_addc_u32 s3, s25, -1
	s_cmp_eq_u32 s61, 60
	s_cselect_b32 s29, s17, s3
	s_cselect_b32 s28, s33, s2
	s_cselect_b32 s3, s15, s60
	s_cselect_b32 s2, s58, s59
	v_lshl_add_u64 v[146:147], s[24:25], 0, v[138:139]
	s_add_i32 m0, s19, 0xc000
	ds_read_b128 v[200:203], v161
	ds_read_b128 v[204:207], v161 offset:1024
	ds_read_b128 v[208:211], v161 offset:2048
	ds_read_b128 v[212:215], v161 offset:3072
	ds_read_b128 v[216:219], v161 offset:4096
	ds_read_b128 v[220:223], v161 offset:5120
	ds_read_b128 v[224:227], v161 offset:6144
	ds_read_b128 v[228:231], v161 offset:7168
	global_load_lds_dwordx4 v[146:147], off
	v_lshl_add_u64 v[146:147], s[24:25], 0, v[140:141]
	s_add_i32 m0, s19, 0xe000
	s_nop 0
	global_load_lds_dwordx4 v[146:147], off
	s_waitcnt vmcnt(8)
	s_waitcnt lgkmcnt(0)
	s_barrier
	s_setprio 1
	s_waitcnt lgkmcnt(0)
	v_mfma_f32_16x16x32_bf16 v[118:121], v[142:145], v[200:203], v[118:121]
	v_mfma_f32_16x16x32_bf16 v[114:117], v[168:171], v[200:203], v[114:117]
	v_mfma_f32_16x16x32_bf16 v[102:105], v[142:145], v[208:211], v[102:105]
	v_mfma_f32_16x16x32_bf16 v[98:101], v[168:171], v[208:211], v[98:101]
	v_mfma_f32_16x16x32_bf16 v[86:89], v[142:145], v[216:219], v[86:89]
	v_mfma_f32_16x16x32_bf16 v[82:85], v[168:171], v[216:219], v[82:85]
	v_mfma_f32_16x16x32_bf16 v[70:73], v[142:145], v[224:227], v[70:73]
	v_mfma_f32_16x16x32_bf16 v[66:69], v[168:171], v[224:227], v[66:69]
	v_mfma_f32_16x16x32_bf16 v[118:121], v[164:167], v[204:207], v[118:121]
	v_mfma_f32_16x16x32_bf16 v[114:117], v[172:175], v[204:207], v[114:117]
	v_mfma_f32_16x16x32_bf16 v[102:105], v[164:167], v[212:215], v[102:105]
	v_mfma_f32_16x16x32_bf16 v[98:101], v[172:175], v[212:215], v[98:101]
	v_mfma_f32_16x16x32_bf16 v[86:89], v[164:167], v[220:223], v[86:89]
	v_mfma_f32_16x16x32_bf16 v[82:85], v[172:175], v[220:223], v[82:85]
	v_mfma_f32_16x16x32_bf16 v[70:73], v[164:167], v[228:231], v[70:73]
	v_mfma_f32_16x16x32_bf16 v[66:69], v[172:175], v[228:231], v[66:69]
	s_setprio 0
	s_setprio 1
	v_mfma_f32_16x16x32_bf16 v[126:129], v[176:179], v[200:203], v[126:129]
	v_mfma_f32_16x16x32_bf16 v[122:125], v[192:195], v[200:203], v[122:125]
	v_mfma_f32_16x16x32_bf16 v[110:113], v[176:179], v[208:211], v[110:113]
	v_mfma_f32_16x16x32_bf16 v[106:109], v[192:195], v[208:211], v[106:109]
	v_mfma_f32_16x16x32_bf16 v[94:97], v[176:179], v[216:219], v[94:97]
	v_mfma_f32_16x16x32_bf16 v[90:93], v[192:195], v[216:219], v[90:93]
	v_mfma_f32_16x16x32_bf16 v[78:81], v[176:179], v[224:227], v[78:81]
	v_mfma_f32_16x16x32_bf16 v[74:77], v[192:195], v[224:227], v[74:77]
	v_mfma_f32_16x16x32_bf16 v[126:129], v[180:183], v[204:207], v[126:129]
	v_mfma_f32_16x16x32_bf16 v[122:125], v[196:199], v[204:207], v[122:125]
	v_mfma_f32_16x16x32_bf16 v[110:113], v[180:183], v[212:215], v[110:113]
	v_mfma_f32_16x16x32_bf16 v[106:109], v[196:199], v[212:215], v[106:109]
	v_mfma_f32_16x16x32_bf16 v[94:97], v[180:183], v[220:223], v[94:97]
	v_mfma_f32_16x16x32_bf16 v[90:93], v[196:199], v[220:223], v[90:93]
	v_mfma_f32_16x16x32_bf16 v[78:81], v[180:183], v[228:231], v[78:81]
	v_mfma_f32_16x16x32_bf16 v[74:77], v[196:199], v[228:231], v[74:77]
	s_setprio 0
	s_barrier
	s_add_i32 s62, s55, s42
	v_lshl_add_u64 v[146:147], s[2:3], 0, v[132:133]
	s_mov_b32 m0, s62
	ds_read_b128 v[200:203], v161 offset:16384
	ds_read_b128 v[204:207], v161 offset:17408
	ds_read_b128 v[208:211], v161 offset:18432
	ds_read_b128 v[212:215], v161 offset:19456
	ds_read_b128 v[216:219], v161 offset:20480
	ds_read_b128 v[220:223], v161 offset:21504
	ds_read_b128 v[224:227], v161 offset:22528
	ds_read_b128 v[228:231], v161 offset:23552
	global_load_lds_dwordx4 v[146:147], off
	s_add_i32 m0, s62, 0x2000
	s_add_u32 s62, s2, 0x100000
	v_lshl_add_u64 v[232:233], s[2:3], 0, v[134:135]
	s_addc_u32 s63, s3, 0
	s_add_i32 s64, s56, s42
	global_load_lds_dwordx4 v[232:233], off
	v_lshl_add_u64 v[234:235], s[62:63], 0, v[132:133]
	s_mov_b32 m0, s64
	v_lshl_add_u64 v[236:237], s[28:29], 0, v[136:137]
	global_load_lds_dwordx4 v[234:235], off
	v_lshl_add_u64 v[234:235], s[62:63], 0, v[134:135]
	s_add_i32 m0, s64, 0x2000
	s_nop 0
	global_load_lds_dwordx4 v[234:235], off
	v_lshl_add_u64 v[234:235], s[28:29], 0, v[130:131]
	s_mov_b32 m0, s19
	s_nop 0
	global_load_lds_dwordx4 v[234:235], off
	s_mov_b32 m0, s23
	s_nop 0
	global_load_lds_dwordx4 v[236:237], off
	s_waitcnt vmcnt(8)
	s_waitcnt lgkmcnt(0)
	s_barrier
	s_setprio 1
	s_waitcnt lgkmcnt(0)
	v_mfma_f32_16x16x32_bf16 v[54:57], v[142:145], v[200:203], v[54:57]
	v_mfma_f32_16x16x32_bf16 v[50:53], v[168:171], v[200:203], v[50:53]
	v_mfma_f32_16x16x32_bf16 v[38:41], v[142:145], v[208:211], v[38:41]
	v_mfma_f32_16x16x32_bf16 v[34:37], v[168:171], v[208:211], v[34:37]
	v_mfma_f32_16x16x32_bf16 v[22:25], v[142:145], v[216:219], v[22:25]
	v_mfma_f32_16x16x32_bf16 v[18:21], v[168:171], v[216:219], v[18:21]
	v_mfma_f32_16x16x32_bf16 v[6:9], v[142:145], v[224:227], v[6:9]
	v_mfma_f32_16x16x32_bf16 v[2:5], v[168:171], v[224:227], v[2:5]
	v_mfma_f32_16x16x32_bf16 v[54:57], v[164:167], v[204:207], v[54:57]
	v_mfma_f32_16x16x32_bf16 v[50:53], v[172:175], v[204:207], v[50:53]
	v_mfma_f32_16x16x32_bf16 v[38:41], v[164:167], v[212:215], v[38:41]
	v_mfma_f32_16x16x32_bf16 v[34:37], v[172:175], v[212:215], v[34:37]
	v_mfma_f32_16x16x32_bf16 v[22:25], v[164:167], v[220:223], v[22:25]
	v_mfma_f32_16x16x32_bf16 v[18:21], v[172:175], v[220:223], v[18:21]
	v_mfma_f32_16x16x32_bf16 v[6:9], v[164:167], v[228:231], v[6:9]
	v_mfma_f32_16x16x32_bf16 v[2:5], v[172:175], v[228:231], v[2:5]
	s_setprio 0
	s_setprio 1
	v_mfma_f32_16x16x32_bf16 v[62:65], v[176:179], v[200:203], v[62:65]
	v_mfma_f32_16x16x32_bf16 v[58:61], v[192:195], v[200:203], v[58:61]
	v_mfma_f32_16x16x32_bf16 v[46:49], v[176:179], v[208:211], v[46:49]
	v_mfma_f32_16x16x32_bf16 v[42:45], v[192:195], v[208:211], v[42:45]
	v_mfma_f32_16x16x32_bf16 v[30:33], v[176:179], v[216:219], v[30:33]
	v_mfma_f32_16x16x32_bf16 v[26:29], v[192:195], v[216:219], v[26:29]
	v_mfma_f32_16x16x32_bf16 v[14:17], v[176:179], v[224:227], v[14:17]
	v_mfma_f32_16x16x32_bf16 v[10:13], v[192:195], v[224:227], v[10:13]
	v_mfma_f32_16x16x32_bf16 v[62:65], v[180:183], v[204:207], v[62:65]
	v_mfma_f32_16x16x32_bf16 v[58:61], v[196:199], v[204:207], v[58:61]
	v_mfma_f32_16x16x32_bf16 v[46:49], v[180:183], v[212:215], v[46:49]
	v_mfma_f32_16x16x32_bf16 v[42:45], v[196:199], v[212:215], v[42:45]
	v_mfma_f32_16x16x32_bf16 v[30:33], v[180:183], v[220:223], v[30:33]
	v_mfma_f32_16x16x32_bf16 v[26:29], v[196:199], v[220:223], v[26:29]
	v_mfma_f32_16x16x32_bf16 v[14:17], v[180:183], v[228:231], v[14:17]
	v_mfma_f32_16x16x32_bf16 v[10:13], v[196:199], v[228:231], v[10:13]
	s_setprio 0
	s_barrier
	s_add_i32 s62, 0, 0x18000
	v_add_u32_e32 v163, s62, v157
	s_add_i32 s63, 0, 0x1c000
	ds_read_b128 v[142:145], v163
	ds_read_b128 v[164:167], v163 offset:1024
	ds_read_b128 v[168:171], v163 offset:2048
	ds_read_b128 v[172:175], v163 offset:3072
	v_add_u32_e32 v163, s63, v157
	ds_read_b128 v[176:179], v163
	ds_read_b128 v[180:183], v163 offset:1024
	ds_read_b128 v[192:195], v163 offset:2048
	ds_read_b128 v[196:199], v163 offset:3072
	s_add_u32 s28, s28, 0x100000
	s_addc_u32 s29, s29, 0
	s_mov_b32 m0, s43
	v_lshl_add_u64 v[238:239], s[28:29], 0, v[130:131]
	ds_read_b128 v[200:203], v161 offset:32768
	ds_read_b128 v[204:207], v161 offset:33792
	ds_read_b128 v[208:211], v161 offset:34816
	ds_read_b128 v[212:215], v161 offset:35840
	ds_read_b128 v[216:219], v161 offset:36864
	ds_read_b128 v[220:223], v161 offset:37888
	ds_read_b128 v[224:227], v161 offset:38912
	ds_read_b128 v[228:231], v161 offset:39936
	global_load_lds_dwordx4 v[238:239], off
	v_lshl_add_u64 v[238:239], s[28:29], 0, v[136:137]
	s_mov_b32 m0, s44
	s_nop 0
	global_load_lds_dwordx4 v[238:239], off
	s_waitcnt vmcnt(8)
	s_waitcnt lgkmcnt(0)
	s_barrier
	s_setprio 1
	s_waitcnt lgkmcnt(0)
	v_mfma_f32_16x16x32_bf16 v[118:121], v[142:145], v[200:203], v[118:121]
	v_mfma_f32_16x16x32_bf16 v[114:117], v[168:171], v[200:203], v[114:117]
	v_mfma_f32_16x16x32_bf16 v[102:105], v[142:145], v[208:211], v[102:105]
	v_mfma_f32_16x16x32_bf16 v[98:101], v[168:171], v[208:211], v[98:101]
	v_mfma_f32_16x16x32_bf16 v[86:89], v[142:145], v[216:219], v[86:89]
	v_mfma_f32_16x16x32_bf16 v[82:85], v[168:171], v[216:219], v[82:85]
	v_mfma_f32_16x16x32_bf16 v[70:73], v[142:145], v[224:227], v[70:73]
	v_mfma_f32_16x16x32_bf16 v[66:69], v[168:171], v[224:227], v[66:69]
	v_mfma_f32_16x16x32_bf16 v[118:121], v[164:167], v[204:207], v[118:121]
	v_mfma_f32_16x16x32_bf16 v[114:117], v[172:175], v[204:207], v[114:117]
	v_mfma_f32_16x16x32_bf16 v[102:105], v[164:167], v[212:215], v[102:105]
	v_mfma_f32_16x16x32_bf16 v[98:101], v[172:175], v[212:215], v[98:101]
	v_mfma_f32_16x16x32_bf16 v[86:89], v[164:167], v[220:223], v[86:89]
	v_mfma_f32_16x16x32_bf16 v[82:85], v[172:175], v[220:223], v[82:85]
	v_mfma_f32_16x16x32_bf16 v[70:73], v[164:167], v[228:231], v[70:73]
	v_mfma_f32_16x16x32_bf16 v[66:69], v[172:175], v[228:231], v[66:69]
	s_setprio 0
	s_setprio 1
	v_mfma_f32_16x16x32_bf16 v[126:129], v[176:179], v[200:203], v[126:129]
	v_mfma_f32_16x16x32_bf16 v[122:125], v[192:195], v[200:203], v[122:125]
	v_mfma_f32_16x16x32_bf16 v[110:113], v[176:179], v[208:211], v[110:113]
	v_mfma_f32_16x16x32_bf16 v[106:109], v[192:195], v[208:211], v[106:109]
	v_mfma_f32_16x16x32_bf16 v[94:97], v[176:179], v[216:219], v[94:97]
	v_mfma_f32_16x16x32_bf16 v[90:93], v[192:195], v[216:219], v[90:93]
	v_mfma_f32_16x16x32_bf16 v[78:81], v[176:179], v[224:227], v[78:81]
	v_mfma_f32_16x16x32_bf16 v[74:77], v[192:195], v[224:227], v[74:77]
	v_mfma_f32_16x16x32_bf16 v[126:129], v[180:183], v[204:207], v[126:129]
	v_mfma_f32_16x16x32_bf16 v[122:125], v[196:199], v[204:207], v[122:125]
	v_mfma_f32_16x16x32_bf16 v[110:113], v[180:183], v[212:215], v[110:113]
	v_mfma_f32_16x16x32_bf16 v[106:109], v[196:199], v[212:215], v[106:109]
	v_mfma_f32_16x16x32_bf16 v[94:97], v[180:183], v[220:223], v[94:97]
	v_mfma_f32_16x16x32_bf16 v[90:93], v[196:199], v[220:223], v[90:93]
	v_mfma_f32_16x16x32_bf16 v[78:81], v[180:183], v[228:231], v[78:81]
	v_mfma_f32_16x16x32_bf16 v[74:77], v[196:199], v[228:231], v[74:77]
	s_setprio 0
	s_barrier
	s_add_i32 s28, s62, s42
	v_lshl_add_u64 v[146:147], v[146:147], 0, s[10:11]
	s_mov_b32 m0, s28
	ds_read_b128 v[200:203], v161 offset:49152
	ds_read_b128 v[204:207], v161 offset:50176
	ds_read_b128 v[208:211], v161 offset:51200
	ds_read_b128 v[212:215], v161 offset:52224
	ds_read_b128 v[216:219], v161 offset:53248
	ds_read_b128 v[220:223], v161 offset:54272
	ds_read_b128 v[224:227], v161 offset:55296
	ds_read_b128 v[228:231], v161 offset:56320
	global_load_lds_dwordx4 v[146:147], off
	s_add_i32 m0, s28, 0x2000
	s_add_u32 s2, s2, 0x100080
	v_lshl_add_u64 v[146:147], v[232:233], 0, s[10:11]
	s_addc_u32 s3, s3, 0
	s_add_i32 s28, s63, s42
	global_load_lds_dwordx4 v[146:147], off
	v_lshl_add_u64 v[146:147], s[2:3], 0, v[132:133]
	s_mov_b32 m0, s28
	s_nop 0
	global_load_lds_dwordx4 v[146:147], off
	v_lshl_add_u64 v[146:147], s[2:3], 0, v[134:135]
	s_add_i32 m0, s28, 0x2000
	s_nop 0
	global_load_lds_dwordx4 v[146:147], off
	v_lshl_add_u64 v[146:147], v[234:235], 0, s[10:11]
	s_mov_b32 m0, s46
	s_nop 0
	global_load_lds_dwordx4 v[146:147], off
	v_lshl_add_u64 v[146:147], v[236:237], 0, s[10:11]
	s_mov_b32 m0, s47
	s_nop 0
	global_load_lds_dwordx4 v[146:147], off
	s_waitcnt vmcnt(8)
	s_cmp_lg_u32 s61, 60
	s_cbranch_scc1 .Lssq_skip_1
	v_lshl_add_u32 v146, s22, 8, v153
	v_ashrrev_i32_e32 v147, 31, v146
	v_lshl_add_u64 v[146:147], v[146:147], 2, s[4:5]
	global_load_dword v241, v[146:147], off
	global_load_dword v242, v[146:147], off offset:64
	global_load_dword v243, v[146:147], off offset:128
	global_load_dword v244, v[146:147], off offset:192
	global_load_dword v245, v[146:147], off offset:512
	global_load_dword v246, v[146:147], off offset:576
	global_load_dword v247, v[146:147], off offset:640
	global_load_dword v248, v[146:147], off offset:704
.Lssq_skip_1:
	s_waitcnt lgkmcnt(0)
	s_barrier
	s_setprio 1
	s_waitcnt lgkmcnt(0)
	v_mfma_f32_16x16x32_bf16 v[54:57], v[142:145], v[200:203], v[54:57]
	v_mfma_f32_16x16x32_bf16 v[50:53], v[168:171], v[200:203], v[50:53]
	v_mfma_f32_16x16x32_bf16 v[38:41], v[142:145], v[208:211], v[38:41]
	v_mfma_f32_16x16x32_bf16 v[34:37], v[168:171], v[208:211], v[34:37]
	v_mfma_f32_16x16x32_bf16 v[22:25], v[142:145], v[216:219], v[22:25]
	v_mfma_f32_16x16x32_bf16 v[18:21], v[168:171], v[216:219], v[18:21]
	v_mfma_f32_16x16x32_bf16 v[6:9], v[142:145], v[224:227], v[6:9]
	v_mfma_f32_16x16x32_bf16 v[2:5], v[168:171], v[224:227], v[2:5]
	v_mfma_f32_16x16x32_bf16 v[54:57], v[164:167], v[204:207], v[54:57]
	v_mfma_f32_16x16x32_bf16 v[50:53], v[172:175], v[204:207], v[50:53]
	v_mfma_f32_16x16x32_bf16 v[38:41], v[164:167], v[212:215], v[38:41]
	v_mfma_f32_16x16x32_bf16 v[34:37], v[172:175], v[212:215], v[34:37]
	v_mfma_f32_16x16x32_bf16 v[22:25], v[164:167], v[220:223], v[22:25]
	v_mfma_f32_16x16x32_bf16 v[18:21], v[172:175], v[220:223], v[18:21]
	v_mfma_f32_16x16x32_bf16 v[6:9], v[164:167], v[228:231], v[6:9]
	v_mfma_f32_16x16x32_bf16 v[2:5], v[172:175], v[228:231], v[2:5]
	s_setprio 0
	s_setprio 1
	v_mfma_f32_16x16x32_bf16 v[62:65], v[176:179], v[200:203], v[62:65]
	v_mfma_f32_16x16x32_bf16 v[58:61], v[192:195], v[200:203], v[58:61]
	v_mfma_f32_16x16x32_bf16 v[46:49], v[176:179], v[208:211], v[46:49]
	v_mfma_f32_16x16x32_bf16 v[42:45], v[192:195], v[208:211], v[42:45]
	v_mfma_f32_16x16x32_bf16 v[30:33], v[176:179], v[216:219], v[30:33]
	v_mfma_f32_16x16x32_bf16 v[26:29], v[192:195], v[216:219], v[26:29]
	v_mfma_f32_16x16x32_bf16 v[14:17], v[176:179], v[224:227], v[14:17]
	v_mfma_f32_16x16x32_bf16 v[10:13], v[192:195], v[224:227], v[10:13]
	v_mfma_f32_16x16x32_bf16 v[62:65], v[180:183], v[204:207], v[62:65]
	v_mfma_f32_16x16x32_bf16 v[58:61], v[196:199], v[204:207], v[58:61]
	v_mfma_f32_16x16x32_bf16 v[46:49], v[180:183], v[212:215], v[46:49]
	v_mfma_f32_16x16x32_bf16 v[42:45], v[196:199], v[212:215], v[42:45]
	v_mfma_f32_16x16x32_bf16 v[30:33], v[180:183], v[220:223], v[30:33]
	v_mfma_f32_16x16x32_bf16 v[26:29], v[196:199], v[220:223], v[26:29]
	v_mfma_f32_16x16x32_bf16 v[14:17], v[180:183], v[228:231], v[14:17]
	v_mfma_f32_16x16x32_bf16 v[10:13], v[196:199], v[228:231], v[10:13]
	s_setprio 0
	s_barrier
	s_add_i32 s61, s61, 2
	s_add_u32 s24, s24, 0x100
	s_addc_u32 s25, s25, 0
	s_add_u32 s59, s59, 0x100
	s_addc_u32 s60, s60, 0
	s_cmp_gt_u32 s61, 61
	s_cbranch_scc0 .LBB0_1333
	s_and_b64 vcc, exec, s[12:13]
	s_cbranch_vccz .LBB0_1336
	s_barrier
.LBB0_1336:
	v_lshl_add_u32 v142, s22, 8, v153
	v_ashrrev_i32_e32 v143, 31, v142
	v_lshl_add_u64 v[146:147], v[142:143], 2, s[4:5]
	v_lshl_or_b32 v144, s18, 7, v158
	v_ashrrev_i32_e32 v145, 31, v144
	v_mov_b32_e32 v254, 1.0
	v_lshl_add_u64 v[144:145], v[144:145], 1, s[6:7]
	s_andn2_b64 vcc, exec, s[26:27]
	v_mad_i64_i32 v[146:147], s[2:3], v142, s57, v[144:145]
	s_waitcnt vmcnt(7)
	v_fmamk_f32 v251, v241, 0x39800000, v162
	v_rsq_f32_e32 v251, v251
	v_pk_mul_f32 v[126:127], v[118:119], v[126:127]
	v_pk_mul_f32 v[128:129], v[120:121], v[128:129]
	v_pk_mul_f32 v[122:123], v[114:115], v[122:123]
	v_pk_mul_f32 v[124:125], v[116:117], v[124:125]
	v_mul_f32_e32 v250, 0xbfb8aa3b, v251
	v_mul_f32_e32 v252, v251, v251
	v_pk_mul_f32 v[118:119], v[118:119], v[250:251] op_sel_hi:[1,0]
	v_pk_mul_f32 v[120:121], v[120:121], v[250:251] op_sel_hi:[1,0]
	v_pk_mul_f32 v[114:115], v[114:115], v[250:251] op_sel_hi:[1,0]
	v_pk_mul_f32 v[116:117], v[116:117], v[250:251] op_sel_hi:[1,0]
	v_exp_f32_e32 v118, v118
	v_exp_f32_e32 v119, v119
	v_exp_f32_e32 v120, v120
	v_exp_f32_e32 v121, v121
	v_exp_f32_e32 v114, v114
	v_exp_f32_e32 v115, v115
	v_exp_f32_e32 v116, v116
	v_exp_f32_e32 v117, v117
	v_pk_add_f32 v[118:119], v[118:119], v[254:255] op_sel_hi:[1,0]
	v_pk_add_f32 v[120:121], v[120:121], v[254:255] op_sel_hi:[1,0]
	v_pk_add_f32 v[114:115], v[114:115], v[254:255] op_sel_hi:[1,0]
	v_pk_add_f32 v[116:117], v[116:117], v[254:255] op_sel_hi:[1,0]
	v_rcp_f32_e32 v118, v118
	v_rcp_f32_e32 v119, v119
	v_rcp_f32_e32 v120, v120
	v_rcp_f32_e32 v121, v121
	v_rcp_f32_e32 v114, v114
	v_rcp_f32_e32 v115, v115
	v_rcp_f32_e32 v116, v116
	v_rcp_f32_e32 v117, v117
	v_pk_mul_f32 v[118:119], v[118:119], v[252:253] op_sel_hi:[1,0]
	v_pk_mul_f32 v[120:121], v[120:121], v[252:253] op_sel_hi:[1,0]
	v_pk_mul_f32 v[114:115], v[114:115], v[252:253] op_sel_hi:[1,0]
	v_pk_mul_f32 v[116:117], v[116:117], v[252:253] op_sel_hi:[1,0]
	v_pk_mul_f32 v[118:119], v[126:127], v[118:119]
	v_pk_mul_f32 v[120:121], v[128:129], v[120:121]
	v_pk_mul_f32 v[114:115], v[122:123], v[114:115]
	v_pk_mul_f32 v[116:117], v[124:125], v[116:117]
	v_cvt_pk_bf16_f32 v122, v118, v119
	v_cvt_pk_bf16_f32 v123, v120, v121
	v_cvt_pk_bf16_f32 v124, v114, v115
	v_cvt_pk_bf16_f32 v125, v116, v117
	global_store_dwordx4 v[146:147], v[122:125], off
	v_add_u32_e32 v253, 16, v142
	v_mad_i64_i32 v[146:147], s[2:3], v253, s57, v[144:145]
	s_waitcnt vmcnt(6)
	v_fmamk_f32 v251, v242, 0x39800000, v162
	v_rsq_f32_e32 v251, v251
	v_pk_mul_f32 v[110:111], v[102:103], v[110:111]
	v_pk_mul_f32 v[112:113], v[104:105], v[112:113]
	v_pk_mul_f32 v[106:107], v[98:99], v[106:107]
	v_pk_mul_f32 v[108:109], v[100:101], v[108:109]
	v_mul_f32_e32 v250, 0xbfb8aa3b, v251
	v_mul_f32_e32 v252, v251, v251
	v_pk_mul_f32 v[102:103], v[102:103], v[250:251] op_sel_hi:[1,0]
	v_pk_mul_f32 v[104:105], v[104:105], v[250:251] op_sel_hi:[1,0]
	v_pk_mul_f32 v[98:99], v[98:99], v[250:251] op_sel_hi:[1,0]
	v_pk_mul_f32 v[100:101], v[100:101], v[250:251] op_sel_hi:[1,0]
	v_exp_f32_e32 v102, v102
	v_exp_f32_e32 v103, v103
	v_exp_f32_e32 v104, v104
	v_exp_f32_e32 v105, v105
	v_exp_f32_e32 v98, v98
	v_exp_f32_e32 v99, v99
	v_exp_f32_e32 v100, v100
	v_exp_f32_e32 v101, v101
	v_pk_add_f32 v[102:103], v[102:103], v[254:255] op_sel_hi:[1,0]
	v_pk_add_f32 v[104:105], v[104:105], v[254:255] op_sel_hi:[1,0]
	v_pk_add_f32 v[98:99], v[98:99], v[254:255] op_sel_hi:[1,0]
	v_pk_add_f32 v[100:101], v[100:101], v[254:255] op_sel_hi:[1,0]
	v_rcp_f32_e32 v102, v102
	v_rcp_f32_e32 v103, v103
	v_rcp_f32_e32 v104, v104
	v_rcp_f32_e32 v105, v105
	v_rcp_f32_e32 v98, v98
	v_rcp_f32_e32 v99, v99
	v_rcp_f32_e32 v100, v100
	v_rcp_f32_e32 v101, v101
	v_pk_mul_f32 v[102:103], v[102:103], v[252:253] op_sel_hi:[1,0]
	v_pk_mul_f32 v[104:105], v[104:105], v[252:253] op_sel_hi:[1,0]
	v_pk_mul_f32 v[98:99], v[98:99], v[252:253] op_sel_hi:[1,0]
	v_pk_mul_f32 v[100:101], v[100:101], v[252:253] op_sel_hi:[1,0]
	v_pk_mul_f32 v[102:103], v[110:111], v[102:103]
	v_pk_mul_f32 v[104:105], v[112:113], v[104:105]
	v_pk_mul_f32 v[98:99], v[106:107], v[98:99]
	v_pk_mul_f32 v[100:101], v[108:109], v[100:101]
	v_cvt_pk_bf16_f32 v106, v102, v103
	v_cvt_pk_bf16_f32 v107, v104, v105
	v_cvt_pk_bf16_f32 v108, v98, v99
	v_cvt_pk_bf16_f32 v109, v100, v101
	global_store_dwordx4 v[146:147], v[106:109], off
	v_add_u32_e32 v253, 32, v142
	v_mad_i64_i32 v[146:147], s[2:3], v253, s57, v[144:145]
	s_waitcnt vmcnt(5)
	v_fmamk_f32 v251, v243, 0x39800000, v162
	v_rsq_f32_e32 v251, v251
	v_pk_mul_f32 v[94:95], v[86:87], v[94:95]
	v_pk_mul_f32 v[96:97], v[88:89], v[96:97]
	v_pk_mul_f32 v[90:91], v[82:83], v[90:91]
	v_pk_mul_f32 v[92:93], v[84:85], v[92:93]
	v_mul_f32_e32 v250, 0xbfb8aa3b, v251
	v_mul_f32_e32 v252, v251, v251
	v_pk_mul_f32 v[86:87], v[86:87], v[250:251] op_sel_hi:[1,0]
	v_pk_mul_f32 v[88:89], v[88:89], v[250:251] op_sel_hi:[1,0]
	v_pk_mul_f32 v[82:83], v[82:83], v[250:251] op_sel_hi:[1,0]
	v_pk_mul_f32 v[84:85], v[84:85], v[250:251] op_sel_hi:[1,0]
	v_exp_f32_e32 v86, v86
	v_exp_f32_e32 v87, v87
	v_exp_f32_e32 v88, v88
	v_exp_f32_e32 v89, v89
	v_exp_f32_e32 v82, v82
	v_exp_f32_e32 v83, v83
	v_exp_f32_e32 v84, v84
	v_exp_f32_e32 v85, v85
	v_pk_add_f32 v[86:87], v[86:87], v[254:255] op_sel_hi:[1,0]
	v_pk_add_f32 v[88:89], v[88:89], v[254:255] op_sel_hi:[1,0]
	v_pk_add_f32 v[82:83], v[82:83], v[254:255] op_sel_hi:[1,0]
	v_pk_add_f32 v[84:85], v[84:85], v[254:255] op_sel_hi:[1,0]
	v_rcp_f32_e32 v86, v86
	v_rcp_f32_e32 v87, v87
	v_rcp_f32_e32 v88, v88
	v_rcp_f32_e32 v89, v89
	v_rcp_f32_e32 v82, v82
	v_rcp_f32_e32 v83, v83
	v_rcp_f32_e32 v84, v84
	v_rcp_f32_e32 v85, v85
	v_pk_mul_f32 v[86:87], v[86:87], v[252:253] op_sel_hi:[1,0]
	v_pk_mul_f32 v[88:89], v[88:89], v[252:253] op_sel_hi:[1,0]
	v_pk_mul_f32 v[82:83], v[82:83], v[252:253] op_sel_hi:[1,0]
	v_pk_mul_f32 v[84:85], v[84:85], v[252:253] op_sel_hi:[1,0]
	v_pk_mul_f32 v[86:87], v[94:95], v[86:87]
	v_pk_mul_f32 v[88:89], v[96:97], v[88:89]
	v_pk_mul_f32 v[82:83], v[90:91], v[82:83]
	v_pk_mul_f32 v[84:85], v[92:93], v[84:85]
	v_cvt_pk_bf16_f32 v90, v86, v87
	v_cvt_pk_bf16_f32 v91, v88, v89
	v_cvt_pk_bf16_f32 v92, v82, v83
	v_cvt_pk_bf16_f32 v93, v84, v85
	global_store_dwordx4 v[146:147], v[90:93], off
	v_add_u32_e32 v253, 48, v142
	v_mad_i64_i32 v[146:147], s[2:3], v253, s57, v[144:145]
	s_waitcnt vmcnt(4)
	v_fmamk_f32 v251, v244, 0x39800000, v162
	v_rsq_f32_e32 v251, v251
	v_pk_mul_f32 v[78:79], v[70:71], v[78:79]
	v_pk_mul_f32 v[80:81], v[72:73], v[80:81]
	v_pk_mul_f32 v[74:75], v[66:67], v[74:75]
	v_pk_mul_f32 v[76:77], v[68:69], v[76:77]
	v_mul_f32_e32 v250, 0xbfb8aa3b, v251
	v_mul_f32_e32 v252, v251, v251
	v_pk_mul_f32 v[70:71], v[70:71], v[250:251] op_sel_hi:[1,0]
	v_pk_mul_f32 v[72:73], v[72:73], v[250:251] op_sel_hi:[1,0]
	v_pk_mul_f32 v[66:67], v[66:67], v[250:251] op_sel_hi:[1,0]
	v_pk_mul_f32 v[68:69], v[68:69], v[250:251] op_sel_hi:[1,0]
	v_exp_f32_e32 v70, v70
	v_exp_f32_e32 v71, v71
	v_exp_f32_e32 v72, v72
	v_exp_f32_e32 v73, v73
	v_exp_f32_e32 v66, v66
	v_exp_f32_e32 v67, v67
	v_exp_f32_e32 v68, v68
	v_exp_f32_e32 v69, v69
	v_pk_add_f32 v[70:71], v[70:71], v[254:255] op_sel_hi:[1,0]
	v_pk_add_f32 v[72:73], v[72:73], v[254:255] op_sel_hi:[1,0]
	v_pk_add_f32 v[66:67], v[66:67], v[254:255] op_sel_hi:[1,0]
	v_pk_add_f32 v[68:69], v[68:69], v[254:255] op_sel_hi:[1,0]
	v_rcp_f32_e32 v70, v70
	v_rcp_f32_e32 v71, v71
	v_rcp_f32_e32 v72, v72
	v_rcp_f32_e32 v73, v73
	v_rcp_f32_e32 v66, v66
	v_rcp_f32_e32 v67, v67
	v_rcp_f32_e32 v68, v68
	v_rcp_f32_e32 v69, v69
	v_pk_mul_f32 v[70:71], v[70:71], v[252:253] op_sel_hi:[1,0]
	v_pk_mul_f32 v[72:73], v[72:73], v[252:253] op_sel_hi:[1,0]
	v_pk_mul_f32 v[66:67], v[66:67], v[252:253] op_sel_hi:[1,0]
	v_pk_mul_f32 v[68:69], v[68:69], v[252:253] op_sel_hi:[1,0]
	v_pk_mul_f32 v[70:71], v[78:79], v[70:71]
	v_pk_mul_f32 v[72:73], v[80:81], v[72:73]
	v_pk_mul_f32 v[66:67], v[74:75], v[66:67]
	v_pk_mul_f32 v[68:69], v[76:77], v[68:69]
	v_cvt_pk_bf16_f32 v74, v70, v71
	v_cvt_pk_bf16_f32 v75, v72, v73
	v_cvt_pk_bf16_f32 v76, v66, v67
	v_cvt_pk_bf16_f32 v77, v68, v69
	global_store_dwordx4 v[146:147], v[74:77], off
	v_add_u32_e32 v253, 128, v142
	v_mad_i64_i32 v[146:147], s[2:3], v253, s57, v[144:145]
	s_waitcnt vmcnt(3)
	v_fmamk_f32 v251, v245, 0x39800000, v162
	v_rsq_f32_e32 v251, v251
	v_pk_mul_f32 v[62:63], v[54:55], v[62:63]
	v_pk_mul_f32 v[64:65], v[56:57], v[64:65]
	v_pk_mul_f32 v[58:59], v[50:51], v[58:59]
	v_pk_mul_f32 v[60:61], v[52:53], v[60:61]
	v_mul_f32_e32 v250, 0xbfb8aa3b, v251
	v_mul_f32_e32 v252, v251, v251
	v_pk_mul_f32 v[54:55], v[54:55], v[250:251] op_sel_hi:[1,0]
	v_pk_mul_f32 v[56:57], v[56:57], v[250:251] op_sel_hi:[1,0]
	v_pk_mul_f32 v[50:51], v[50:51], v[250:251] op_sel_hi:[1,0]
	v_pk_mul_f32 v[52:53], v[52:53], v[250:251] op_sel_hi:[1,0]
	v_exp_f32_e32 v54, v54
	v_exp_f32_e32 v55, v55
	v_exp_f32_e32 v56, v56
	v_exp_f32_e32 v57, v57
	v_exp_f32_e32 v50, v50
	v_exp_f32_e32 v51, v51
	v_exp_f32_e32 v52, v52
	v_exp_f32_e32 v53, v53
	v_pk_add_f32 v[54:55], v[54:55], v[254:255] op_sel_hi:[1,0]
	v_pk_add_f32 v[56:57], v[56:57], v[254:255] op_sel_hi:[1,0]
	v_pk_add_f32 v[50:51], v[50:51], v[254:255] op_sel_hi:[1,0]
	v_pk_add_f32 v[52:53], v[52:53], v[254:255] op_sel_hi:[1,0]
	v_rcp_f32_e32 v54, v54
	v_rcp_f32_e32 v55, v55
	v_rcp_f32_e32 v56, v56
	v_rcp_f32_e32 v57, v57
	v_rcp_f32_e32 v50, v50
	v_rcp_f32_e32 v51, v51
	v_rcp_f32_e32 v52, v52
	v_rcp_f32_e32 v53, v53
	v_pk_mul_f32 v[54:55], v[54:55], v[252:253] op_sel_hi:[1,0]
	v_pk_mul_f32 v[56:57], v[56:57], v[252:253] op_sel_hi:[1,0]
	v_pk_mul_f32 v[50:51], v[50:51], v[252:253] op_sel_hi:[1,0]
	v_pk_mul_f32 v[52:53], v[52:53], v[252:253] op_sel_hi:[1,0]
	v_pk_mul_f32 v[54:55], v[62:63], v[54:55]
	v_pk_mul_f32 v[56:57], v[64:65], v[56:57]
	v_pk_mul_f32 v[50:51], v[58:59], v[50:51]
	v_pk_mul_f32 v[52:53], v[60:61], v[52:53]
	v_cvt_pk_bf16_f32 v58, v54, v55
	v_cvt_pk_bf16_f32 v59, v56, v57
	v_cvt_pk_bf16_f32 v60, v50, v51
	v_cvt_pk_bf16_f32 v61, v52, v53
	global_store_dwordx4 v[146:147], v[58:61], off
	v_add_u32_e32 v253, 144, v142
	v_mad_i64_i32 v[146:147], s[2:3], v253, s57, v[144:145]
	s_waitcnt vmcnt(2)
	v_fmamk_f32 v251, v246, 0x39800000, v162
	v_rsq_f32_e32 v251, v251
	v_pk_mul_f32 v[46:47], v[38:39], v[46:47]
	v_pk_mul_f32 v[48:49], v[40:41], v[48:49]
	v_pk_mul_f32 v[42:43], v[34:35], v[42:43]
	v_pk_mul_f32 v[44:45], v[36:37], v[44:45]
	v_mul_f32_e32 v250, 0xbfb8aa3b, v251
	v_mul_f32_e32 v252, v251, v251
	v_pk_mul_f32 v[38:39], v[38:39], v[250:251] op_sel_hi:[1,0]
	v_pk_mul_f32 v[40:41], v[40:41], v[250:251] op_sel_hi:[1,0]
	v_pk_mul_f32 v[34:35], v[34:35], v[250:251] op_sel_hi:[1,0]
	v_pk_mul_f32 v[36:37], v[36:37], v[250:251] op_sel_hi:[1,0]
	v_exp_f32_e32 v38, v38
	v_exp_f32_e32 v39, v39
	v_exp_f32_e32 v40, v40
	v_exp_f32_e32 v41, v41
	v_exp_f32_e32 v34, v34
	v_exp_f32_e32 v35, v35
	v_exp_f32_e32 v36, v36
	v_exp_f32_e32 v37, v37
	v_pk_add_f32 v[38:39], v[38:39], v[254:255] op_sel_hi:[1,0]
	v_pk_add_f32 v[40:41], v[40:41], v[254:255] op_sel_hi:[1,0]
	v_pk_add_f32 v[34:35], v[34:35], v[254:255] op_sel_hi:[1,0]
	v_pk_add_f32 v[36:37], v[36:37], v[254:255] op_sel_hi:[1,0]
	v_rcp_f32_e32 v38, v38
	v_rcp_f32_e32 v39, v39
	v_rcp_f32_e32 v40, v40
	v_rcp_f32_e32 v41, v41
	v_rcp_f32_e32 v34, v34
	v_rcp_f32_e32 v35, v35
	v_rcp_f32_e32 v36, v36
	v_rcp_f32_e32 v37, v37
	v_pk_mul_f32 v[38:39], v[38:39], v[252:253] op_sel_hi:[1,0]
	v_pk_mul_f32 v[40:41], v[40:41], v[252:253] op_sel_hi:[1,0]
	v_pk_mul_f32 v[34:35], v[34:35], v[252:253] op_sel_hi:[1,0]
	v_pk_mul_f32 v[36:37], v[36:37], v[252:253] op_sel_hi:[1,0]
	v_pk_mul_f32 v[38:39], v[46:47], v[38:39]
	v_pk_mul_f32 v[40:41], v[48:49], v[40:41]
	v_pk_mul_f32 v[34:35], v[42:43], v[34:35]
	v_pk_mul_f32 v[36:37], v[44:45], v[36:37]
	v_cvt_pk_bf16_f32 v42, v38, v39
	v_cvt_pk_bf16_f32 v43, v40, v41
	v_cvt_pk_bf16_f32 v44, v34, v35
	v_cvt_pk_bf16_f32 v45, v36, v37
	global_store_dwordx4 v[146:147], v[42:45], off
	v_add_u32_e32 v253, 160, v142
	v_mad_i64_i32 v[146:147], s[2:3], v253, s57, v[144:145]
	s_waitcnt vmcnt(1)
	v_fmamk_f32 v251, v247, 0x39800000, v162
	v_rsq_f32_e32 v251, v251
	v_pk_mul_f32 v[30:31], v[22:23], v[30:31]
	v_pk_mul_f32 v[32:33], v[24:25], v[32:33]
	v_pk_mul_f32 v[26:27], v[18:19], v[26:27]
	v_pk_mul_f32 v[28:29], v[20:21], v[28:29]
	v_mul_f32_e32 v250, 0xbfb8aa3b, v251
	v_mul_f32_e32 v252, v251, v251
	v_pk_mul_f32 v[22:23], v[22:23], v[250:251] op_sel_hi:[1,0]
	v_pk_mul_f32 v[24:25], v[24:25], v[250:251] op_sel_hi:[1,0]
	v_pk_mul_f32 v[18:19], v[18:19], v[250:251] op_sel_hi:[1,0]
	v_pk_mul_f32 v[20:21], v[20:21], v[250:251] op_sel_hi:[1,0]
	v_exp_f32_e32 v22, v22
	v_exp_f32_e32 v23, v23
	v_exp_f32_e32 v24, v24
	v_exp_f32_e32 v25, v25
	v_exp_f32_e32 v18, v18
	v_exp_f32_e32 v19, v19
	v_exp_f32_e32 v20, v20
	v_exp_f32_e32 v21, v21
	v_pk_add_f32 v[22:23], v[22:23], v[254:255] op_sel_hi:[1,0]
	v_pk_add_f32 v[24:25], v[24:25], v[254:255] op_sel_hi:[1,0]
	v_pk_add_f32 v[18:19], v[18:19], v[254:255] op_sel_hi:[1,0]
	v_pk_add_f32 v[20:21], v[20:21], v[254:255] op_sel_hi:[1,0]
	v_rcp_f32_e32 v22, v22
	v_rcp_f32_e32 v23, v23
	v_rcp_f32_e32 v24, v24
	v_rcp_f32_e32 v25, v25
	v_rcp_f32_e32 v18, v18
	v_rcp_f32_e32 v19, v19
	v_rcp_f32_e32 v20, v20
	v_rcp_f32_e32 v21, v21
	v_pk_mul_f32 v[22:23], v[22:23], v[252:253] op_sel_hi:[1,0]
	v_pk_mul_f32 v[24:25], v[24:25], v[252:253] op_sel_hi:[1,0]
	v_pk_mul_f32 v[18:19], v[18:19], v[252:253] op_sel_hi:[1,0]
	v_pk_mul_f32 v[20:21], v[20:21], v[252:253] op_sel_hi:[1,0]
	v_pk_mul_f32 v[22:23], v[30:31], v[22:23]
	v_pk_mul_f32 v[24:25], v[32:33], v[24:25]
	v_pk_mul_f32 v[18:19], v[26:27], v[18:19]
	v_pk_mul_f32 v[20:21], v[28:29], v[20:21]
	v_cvt_pk_bf16_f32 v26, v22, v23
	v_cvt_pk_bf16_f32 v27, v24, v25
	v_cvt_pk_bf16_f32 v28, v18, v19
	v_cvt_pk_bf16_f32 v29, v20, v21
	global_store_dwordx4 v[146:147], v[26:29], off
	v_add_u32_e32 v253, 176, v142
	v_mad_i64_i32 v[146:147], s[2:3], v253, s57, v[144:145]
	s_mov_b64 s[2:3], -1
	s_waitcnt vmcnt(0)
	v_fmamk_f32 v251, v248, 0x39800000, v162
	v_rsq_f32_e32 v251, v251
	v_pk_mul_f32 v[14:15], v[6:7], v[14:15]
	v_pk_mul_f32 v[16:17], v[8:9], v[16:17]
	v_pk_mul_f32 v[10:11], v[2:3], v[10:11]
	v_pk_mul_f32 v[12:13], v[4:5], v[12:13]
	v_mul_f32_e32 v250, 0xbfb8aa3b, v251
	v_mul_f32_e32 v252, v251, v251
	v_pk_mul_f32 v[6:7], v[6:7], v[250:251] op_sel_hi:[1,0]
	v_pk_mul_f32 v[8:9], v[8:9], v[250:251] op_sel_hi:[1,0]
	v_pk_mul_f32 v[2:3], v[2:3], v[250:251] op_sel_hi:[1,0]
	v_pk_mul_f32 v[4:5], v[4:5], v[250:251] op_sel_hi:[1,0]
	v_exp_f32_e32 v6, v6
	v_exp_f32_e32 v7, v7
	v_exp_f32_e32 v8, v8
	v_exp_f32_e32 v9, v9
	v_exp_f32_e32 v2, v2
	v_exp_f32_e32 v3, v3
	v_exp_f32_e32 v4, v4
	v_exp_f32_e32 v5, v5
	v_pk_add_f32 v[6:7], v[6:7], v[254:255] op_sel_hi:[1,0]
	v_pk_add_f32 v[8:9], v[8:9], v[254:255] op_sel_hi:[1,0]
	v_pk_add_f32 v[2:3], v[2:3], v[254:255] op_sel_hi:[1,0]
	v_pk_add_f32 v[4:5], v[4:5], v[254:255] op_sel_hi:[1,0]
	v_rcp_f32_e32 v6, v6
	v_rcp_f32_e32 v7, v7
	v_rcp_f32_e32 v8, v8
	v_rcp_f32_e32 v9, v9
	v_rcp_f32_e32 v2, v2
	v_rcp_f32_e32 v3, v3
	v_rcp_f32_e32 v4, v4
	v_rcp_f32_e32 v5, v5
	v_pk_mul_f32 v[6:7], v[6:7], v[252:253] op_sel_hi:[1,0]
	v_pk_mul_f32 v[8:9], v[8:9], v[252:253] op_sel_hi:[1,0]
	v_pk_mul_f32 v[2:3], v[2:3], v[252:253] op_sel_hi:[1,0]
	v_pk_mul_f32 v[4:5], v[4:5], v[252:253] op_sel_hi:[1,0]
	v_pk_mul_f32 v[6:7], v[14:15], v[6:7]
	v_pk_mul_f32 v[8:9], v[16:17], v[8:9]
	v_pk_mul_f32 v[2:3], v[10:11], v[2:3]
	v_pk_mul_f32 v[4:5], v[12:13], v[4:5]
	v_cvt_pk_bf16_f32 v10, v6, v7
	v_cvt_pk_bf16_f32 v11, v8, v9
	v_cvt_pk_bf16_f32 v12, v2, v3
	v_cvt_pk_bf16_f32 v13, v4, v5
	global_store_dwordx4 v[146:147], v[10:13], off
	s_cbranch_vccnz .LBB0_1258
	s_andn2_b64 vcc, exec, s[0:1]
	s_cbranch_vccnz .LBB0_1257
	s_barrier
	s_branch .LBB0_1257

.LBB0_1539:
	ds_read_b128 v[142:145], v152
	ds_read_b128 v[162:165], v152 offset:1024
	ds_read_b128 v[166:169], v152 offset:2048
	ds_read_b128 v[170:173], v152 offset:3072
	ds_read_b128 v[174:177], v159
	ds_read_b128 v[178:181], v159 offset:1024
	ds_read_b128 v[192:195], v159 offset:2048
	ds_read_b128 v[196:199], v159 offset:3072
	s_add_u32 s2, s26, 0xfff00080
	s_addc_u32 s3, s27, -1
	s_cmp_eq_u32 s54, 60
	s_cselect_b32 s29, s15, s3
	s_cselect_b32 s28, s33, s2
	s_cselect_b32 s3, s13, s53
	s_cselect_b32 s2, s51, s52
	v_lshl_add_u64 v[146:147], s[26:27], 0, v[138:139]
	s_add_i32 m0, s17, 0xc000
	ds_read_b128 v[200:203], v160
	ds_read_b128 v[204:207], v160 offset:1024
	ds_read_b128 v[208:211], v160 offset:2048
	ds_read_b128 v[212:215], v160 offset:3072
	ds_read_b128 v[216:219], v160 offset:4096
	ds_read_b128 v[220:223], v160 offset:5120
	ds_read_b128 v[224:227], v160 offset:6144
	ds_read_b128 v[228:231], v160 offset:7168
	global_load_lds_dwordx4 v[146:147], off
	v_lshl_add_u64 v[146:147], s[26:27], 0, v[140:141]
	s_add_i32 m0, s17, 0xe000
	s_nop 0
	global_load_lds_dwordx4 v[146:147], off
	s_waitcnt vmcnt(8)
	s_waitcnt lgkmcnt(0)
	s_barrier
	s_setprio 1
	s_waitcnt lgkmcnt(0)
	v_mfma_f32_16x16x32_bf16 v[118:121], v[142:145], v[200:203], v[118:121]
	v_mfma_f32_16x16x32_bf16 v[114:117], v[166:169], v[200:203], v[114:117]
	v_mfma_f32_16x16x32_bf16 v[102:105], v[142:145], v[208:211], v[102:105]
	v_mfma_f32_16x16x32_bf16 v[98:101], v[166:169], v[208:211], v[98:101]
	v_mfma_f32_16x16x32_bf16 v[86:89], v[142:145], v[216:219], v[86:89]
	v_mfma_f32_16x16x32_bf16 v[82:85], v[166:169], v[216:219], v[82:85]
	v_mfma_f32_16x16x32_bf16 v[70:73], v[142:145], v[224:227], v[70:73]
	v_mfma_f32_16x16x32_bf16 v[66:69], v[166:169], v[224:227], v[66:69]
	v_mfma_f32_16x16x32_bf16 v[118:121], v[162:165], v[204:207], v[118:121]
	v_mfma_f32_16x16x32_bf16 v[114:117], v[170:173], v[204:207], v[114:117]
	v_mfma_f32_16x16x32_bf16 v[102:105], v[162:165], v[212:215], v[102:105]
	v_mfma_f32_16x16x32_bf16 v[98:101], v[170:173], v[212:215], v[98:101]
	v_mfma_f32_16x16x32_bf16 v[86:89], v[162:165], v[220:223], v[86:89]
	v_mfma_f32_16x16x32_bf16 v[82:85], v[170:173], v[220:223], v[82:85]
	v_mfma_f32_16x16x32_bf16 v[70:73], v[162:165], v[228:231], v[70:73]
	v_mfma_f32_16x16x32_bf16 v[66:69], v[170:173], v[228:231], v[66:69]
	s_setprio 0
	s_setprio 1
	v_mfma_f32_16x16x32_bf16 v[126:129], v[174:177], v[200:203], v[126:129]
	v_mfma_f32_16x16x32_bf16 v[122:125], v[192:195], v[200:203], v[122:125]
	v_mfma_f32_16x16x32_bf16 v[110:113], v[174:177], v[208:211], v[110:113]
	v_mfma_f32_16x16x32_bf16 v[106:109], v[192:195], v[208:211], v[106:109]
	v_mfma_f32_16x16x32_bf16 v[94:97], v[174:177], v[216:219], v[94:97]
	v_mfma_f32_16x16x32_bf16 v[90:93], v[192:195], v[216:219], v[90:93]
	v_mfma_f32_16x16x32_bf16 v[78:81], v[174:177], v[224:227], v[78:81]
	v_mfma_f32_16x16x32_bf16 v[74:77], v[192:195], v[224:227], v[74:77]
	v_mfma_f32_16x16x32_bf16 v[126:129], v[178:181], v[204:207], v[126:129]
	v_mfma_f32_16x16x32_bf16 v[122:125], v[196:199], v[204:207], v[122:125]
	v_mfma_f32_16x16x32_bf16 v[110:113], v[178:181], v[212:215], v[110:113]
	v_mfma_f32_16x16x32_bf16 v[106:109], v[196:199], v[212:215], v[106:109]
	v_mfma_f32_16x16x32_bf16 v[94:97], v[178:181], v[220:223], v[94:97]
	v_mfma_f32_16x16x32_bf16 v[90:93], v[196:199], v[220:223], v[90:93]
	v_mfma_f32_16x16x32_bf16 v[78:81], v[178:181], v[228:231], v[78:81]
	v_mfma_f32_16x16x32_bf16 v[74:77], v[196:199], v[228:231], v[74:77]
	s_setprio 0
	s_barrier
	s_add_i32 s55, s48, s36
	v_lshl_add_u64 v[146:147], s[2:3], 0, v[132:133]
	s_mov_b32 m0, s55
	ds_read_b128 v[200:203], v160 offset:16384
	ds_read_b128 v[204:207], v160 offset:17408
	ds_read_b128 v[208:211], v160 offset:18432
	ds_read_b128 v[212:215], v160 offset:19456
	ds_read_b128 v[216:219], v160 offset:20480
	ds_read_b128 v[220:223], v160 offset:21504
	ds_read_b128 v[224:227], v160 offset:22528
	ds_read_b128 v[228:231], v160 offset:23552
	global_load_lds_dwordx4 v[146:147], off
	s_add_i32 m0, s55, 0x2000
	s_add_u32 s56, s2, 0x100000
	v_lshl_add_u64 v[182:183], s[2:3], 0, v[134:135]
	s_addc_u32 s57, s3, 0
	s_add_i32 s55, s49, s36
	global_load_lds_dwordx4 v[182:183], off
	v_lshl_add_u64 v[232:233], s[56:57], 0, v[132:133]
	s_mov_b32 m0, s55
	v_lshl_add_u64 v[234:235], s[28:29], 0, v[136:137]
	global_load_lds_dwordx4 v[232:233], off
	v_lshl_add_u64 v[232:233], s[56:57], 0, v[134:135]
	s_add_i32 m0, s55, 0x2000
	s_nop 0
	global_load_lds_dwordx4 v[232:233], off
	v_lshl_add_u64 v[232:233], s[28:29], 0, v[130:131]
	s_mov_b32 m0, s17
	s_nop 0
	global_load_lds_dwordx4 v[232:233], off
	s_mov_b32 m0, s19
	s_nop 0
	global_load_lds_dwordx4 v[234:235], off
	s_waitcnt vmcnt(8)
	s_waitcnt lgkmcnt(0)
	s_barrier
	s_setprio 1
	s_waitcnt lgkmcnt(0)
	v_mfma_f32_16x16x32_bf16 v[54:57], v[142:145], v[200:203], v[54:57]
	v_mfma_f32_16x16x32_bf16 v[50:53], v[166:169], v[200:203], v[50:53]
	v_mfma_f32_16x16x32_bf16 v[38:41], v[142:145], v[208:211], v[38:41]
	v_mfma_f32_16x16x32_bf16 v[34:37], v[166:169], v[208:211], v[34:37]
	v_mfma_f32_16x16x32_bf16 v[22:25], v[142:145], v[216:219], v[22:25]
	v_mfma_f32_16x16x32_bf16 v[18:21], v[166:169], v[216:219], v[18:21]
	v_mfma_f32_16x16x32_bf16 v[6:9], v[142:145], v[224:227], v[6:9]
	v_mfma_f32_16x16x32_bf16 v[2:5], v[166:169], v[224:227], v[2:5]
	v_mfma_f32_16x16x32_bf16 v[54:57], v[162:165], v[204:207], v[54:57]
	v_mfma_f32_16x16x32_bf16 v[50:53], v[170:173], v[204:207], v[50:53]
	v_mfma_f32_16x16x32_bf16 v[38:41], v[162:165], v[212:215], v[38:41]
	v_mfma_f32_16x16x32_bf16 v[34:37], v[170:173], v[212:215], v[34:37]
	v_mfma_f32_16x16x32_bf16 v[22:25], v[162:165], v[220:223], v[22:25]
	v_mfma_f32_16x16x32_bf16 v[18:21], v[170:173], v[220:223], v[18:21]
	v_mfma_f32_16x16x32_bf16 v[6:9], v[162:165], v[228:231], v[6:9]
	v_mfma_f32_16x16x32_bf16 v[2:5], v[170:173], v[228:231], v[2:5]
	s_setprio 0
	s_setprio 1
	v_mfma_f32_16x16x32_bf16 v[62:65], v[174:177], v[200:203], v[62:65]
	v_mfma_f32_16x16x32_bf16 v[58:61], v[192:195], v[200:203], v[58:61]
	v_mfma_f32_16x16x32_bf16 v[46:49], v[174:177], v[208:211], v[46:49]
	v_mfma_f32_16x16x32_bf16 v[42:45], v[192:195], v[208:211], v[42:45]
	v_mfma_f32_16x16x32_bf16 v[30:33], v[174:177], v[216:219], v[30:33]
	v_mfma_f32_16x16x32_bf16 v[26:29], v[192:195], v[216:219], v[26:29]
	v_mfma_f32_16x16x32_bf16 v[14:17], v[174:177], v[224:227], v[14:17]
	v_mfma_f32_16x16x32_bf16 v[10:13], v[192:195], v[224:227], v[10:13]
	v_mfma_f32_16x16x32_bf16 v[62:65], v[178:181], v[204:207], v[62:65]
	v_mfma_f32_16x16x32_bf16 v[58:61], v[196:199], v[204:207], v[58:61]
	v_mfma_f32_16x16x32_bf16 v[46:49], v[178:181], v[212:215], v[46:49]
	v_mfma_f32_16x16x32_bf16 v[42:45], v[196:199], v[212:215], v[42:45]
	v_mfma_f32_16x16x32_bf16 v[30:33], v[178:181], v[220:223], v[30:33]
	v_mfma_f32_16x16x32_bf16 v[26:29], v[196:199], v[220:223], v[26:29]
	v_mfma_f32_16x16x32_bf16 v[14:17], v[178:181], v[228:231], v[14:17]
	v_mfma_f32_16x16x32_bf16 v[10:13], v[196:199], v[228:231], v[10:13]
	s_setprio 0
	s_barrier
	s_add_i32 s55, 0, 0x18000
	s_add_i32 s56, 0, 0x1c000
	v_add_u32_e32 v170, s55, v157
	v_add_u32_e32 v191, s56, v157
	ds_read_b128 v[142:145], v170
	ds_read_b128 v[162:165], v170 offset:1024
	ds_read_b128 v[166:169], v170 offset:2048
	ds_read_b128 v[170:173], v170 offset:3072
	ds_read_b128 v[174:177], v191
	ds_read_b128 v[178:181], v191 offset:1024
	ds_read_b128 v[192:195], v191 offset:2048
	ds_read_b128 v[196:199], v191 offset:3072
	s_add_u32 s28, s28, 0x100000
	s_addc_u32 s29, s29, 0
	s_mov_b32 m0, s37
	v_lshl_add_u64 v[236:237], s[28:29], 0, v[130:131]
	ds_read_b128 v[200:203], v160 offset:32768
	ds_read_b128 v[204:207], v160 offset:33792
	ds_read_b128 v[208:211], v160 offset:34816
	ds_read_b128 v[212:215], v160 offset:35840
	ds_read_b128 v[216:219], v160 offset:36864
	ds_read_b128 v[220:223], v160 offset:37888
	ds_read_b128 v[224:227], v160 offset:38912
	ds_read_b128 v[228:231], v160 offset:39936
	global_load_lds_dwordx4 v[236:237], off
	v_lshl_add_u64 v[236:237], s[28:29], 0, v[136:137]
	s_mov_b32 m0, s38
	s_nop 0
	global_load_lds_dwordx4 v[236:237], off
	s_waitcnt vmcnt(8)
	s_waitcnt lgkmcnt(0)
	s_barrier
	s_setprio 1
	s_waitcnt lgkmcnt(0)
	v_mfma_f32_16x16x32_bf16 v[118:121], v[142:145], v[200:203], v[118:121]
	v_mfma_f32_16x16x32_bf16 v[114:117], v[166:169], v[200:203], v[114:117]
	v_mfma_f32_16x16x32_bf16 v[102:105], v[142:145], v[208:211], v[102:105]
	v_mfma_f32_16x16x32_bf16 v[98:101], v[166:169], v[208:211], v[98:101]
	v_mfma_f32_16x16x32_bf16 v[86:89], v[142:145], v[216:219], v[86:89]
	v_mfma_f32_16x16x32_bf16 v[82:85], v[166:169], v[216:219], v[82:85]
	v_mfma_f32_16x16x32_bf16 v[70:73], v[142:145], v[224:227], v[70:73]
	v_mfma_f32_16x16x32_bf16 v[66:69], v[166:169], v[224:227], v[66:69]
	v_mfma_f32_16x16x32_bf16 v[118:121], v[162:165], v[204:207], v[118:121]
	v_mfma_f32_16x16x32_bf16 v[114:117], v[170:173], v[204:207], v[114:117]
	v_mfma_f32_16x16x32_bf16 v[102:105], v[162:165], v[212:215], v[102:105]
	v_mfma_f32_16x16x32_bf16 v[98:101], v[170:173], v[212:215], v[98:101]
	v_mfma_f32_16x16x32_bf16 v[86:89], v[162:165], v[220:223], v[86:89]
	v_mfma_f32_16x16x32_bf16 v[82:85], v[170:173], v[220:223], v[82:85]
	v_mfma_f32_16x16x32_bf16 v[70:73], v[162:165], v[228:231], v[70:73]
	v_mfma_f32_16x16x32_bf16 v[66:69], v[170:173], v[228:231], v[66:69]
	s_setprio 0
	s_setprio 1
	v_mfma_f32_16x16x32_bf16 v[126:129], v[174:177], v[200:203], v[126:129]
	v_mfma_f32_16x16x32_bf16 v[122:125], v[192:195], v[200:203], v[122:125]
	v_mfma_f32_16x16x32_bf16 v[110:113], v[174:177], v[208:211], v[110:113]
	v_mfma_f32_16x16x32_bf16 v[106:109], v[192:195], v[208:211], v[106:109]
	v_mfma_f32_16x16x32_bf16 v[94:97], v[174:177], v[216:219], v[94:97]
	v_mfma_f32_16x16x32_bf16 v[90:93], v[192:195], v[216:219], v[90:93]
	v_mfma_f32_16x16x32_bf16 v[78:81], v[174:177], v[224:227], v[78:81]
	v_mfma_f32_16x16x32_bf16 v[74:77], v[192:195], v[224:227], v[74:77]
	v_mfma_f32_16x16x32_bf16 v[126:129], v[178:181], v[204:207], v[126:129]
	v_mfma_f32_16x16x32_bf16 v[122:125], v[196:199], v[204:207], v[122:125]
	v_mfma_f32_16x16x32_bf16 v[110:113], v[178:181], v[212:215], v[110:113]
	v_mfma_f32_16x16x32_bf16 v[106:109], v[196:199], v[212:215], v[106:109]
	v_mfma_f32_16x16x32_bf16 v[94:97], v[178:181], v[220:223], v[94:97]
	v_mfma_f32_16x16x32_bf16 v[90:93], v[196:199], v[220:223], v[90:93]
	v_mfma_f32_16x16x32_bf16 v[78:81], v[178:181], v[228:231], v[78:81]
	v_mfma_f32_16x16x32_bf16 v[74:77], v[196:199], v[228:231], v[74:77]
	s_setprio 0
	s_barrier
	s_add_i32 s28, s55, s36
	v_lshl_add_u64 v[146:147], v[146:147], 0, s[8:9]
	s_mov_b32 m0, s28
	ds_read_b128 v[200:203], v160 offset:49152
	ds_read_b128 v[204:207], v160 offset:50176
	ds_read_b128 v[208:211], v160 offset:51200
	ds_read_b128 v[212:215], v160 offset:52224
	ds_read_b128 v[216:219], v160 offset:53248
	ds_read_b128 v[220:223], v160 offset:54272
	ds_read_b128 v[224:227], v160 offset:55296
	ds_read_b128 v[228:231], v160 offset:56320
	global_load_lds_dwordx4 v[146:147], off
	s_add_i32 m0, s28, 0x2000
	s_add_u32 s2, s2, 0x100080
	v_lshl_add_u64 v[146:147], v[182:183], 0, s[8:9]
	s_addc_u32 s3, s3, 0
	s_add_i32 s28, s56, s36
	global_load_lds_dwordx4 v[146:147], off
	v_lshl_add_u64 v[146:147], s[2:3], 0, v[132:133]
	s_mov_b32 m0, s28
	s_nop 0
	global_load_lds_dwordx4 v[146:147], off
	v_lshl_add_u64 v[146:147], s[2:3], 0, v[134:135]
	s_add_i32 m0, s28, 0x2000
	s_nop 0
	global_load_lds_dwordx4 v[146:147], off
	v_lshl_add_u64 v[146:147], v[232:233], 0, s[8:9]
	s_mov_b32 m0, s42
	s_nop 0
	global_load_lds_dwordx4 v[146:147], off
	v_lshl_add_u64 v[146:147], v[234:235], 0, s[8:9]
	s_mov_b32 m0, s43
	s_nop 0
	global_load_lds_dwordx4 v[146:147], off
	s_waitcnt vmcnt(8)
	s_cmp_lg_u32 s54, 60
	s_cbranch_scc1 .Lssq_skip_2
	v_lshl_add_u32 v146, s18, 8, v153
	v_ashrrev_i32_e32 v147, 31, v146
	v_lshl_add_u64 v[146:147], v[146:147], 2, s[4:5]
	global_load_dword v241, v[146:147], off
	global_load_dword v242, v[146:147], off offset:64
	global_load_dword v243, v[146:147], off offset:128
	global_load_dword v244, v[146:147], off offset:192
	global_load_dword v245, v[146:147], off offset:512
	global_load_dword v246, v[146:147], off offset:576
	global_load_dword v247, v[146:147], off offset:640
	global_load_dword v248, v[146:147], off offset:704
.Lssq_skip_2:
	s_waitcnt lgkmcnt(0)
	s_barrier
	s_setprio 1
	s_waitcnt lgkmcnt(0)
	v_mfma_f32_16x16x32_bf16 v[54:57], v[142:145], v[200:203], v[54:57]
	v_mfma_f32_16x16x32_bf16 v[50:53], v[166:169], v[200:203], v[50:53]
	v_mfma_f32_16x16x32_bf16 v[38:41], v[142:145], v[208:211], v[38:41]
	v_mfma_f32_16x16x32_bf16 v[34:37], v[166:169], v[208:211], v[34:37]
	v_mfma_f32_16x16x32_bf16 v[22:25], v[142:145], v[216:219], v[22:25]
	v_mfma_f32_16x16x32_bf16 v[18:21], v[166:169], v[216:219], v[18:21]
	v_mfma_f32_16x16x32_bf16 v[6:9], v[142:145], v[224:227], v[6:9]
	v_mfma_f32_16x16x32_bf16 v[2:5], v[166:169], v[224:227], v[2:5]
	v_mfma_f32_16x16x32_bf16 v[54:57], v[162:165], v[204:207], v[54:57]
	v_mfma_f32_16x16x32_bf16 v[50:53], v[170:173], v[204:207], v[50:53]
	v_mfma_f32_16x16x32_bf16 v[38:41], v[162:165], v[212:215], v[38:41]
	v_mfma_f32_16x16x32_bf16 v[34:37], v[170:173], v[212:215], v[34:37]
	v_mfma_f32_16x16x32_bf16 v[22:25], v[162:165], v[220:223], v[22:25]
	v_mfma_f32_16x16x32_bf16 v[18:21], v[170:173], v[220:223], v[18:21]
	v_mfma_f32_16x16x32_bf16 v[6:9], v[162:165], v[228:231], v[6:9]
	v_mfma_f32_16x16x32_bf16 v[2:5], v[170:173], v[228:231], v[2:5]
	s_setprio 0
	s_setprio 1
	v_mfma_f32_16x16x32_bf16 v[62:65], v[174:177], v[200:203], v[62:65]
	v_mfma_f32_16x16x32_bf16 v[58:61], v[192:195], v[200:203], v[58:61]
	v_mfma_f32_16x16x32_bf16 v[46:49], v[174:177], v[208:211], v[46:49]
	v_mfma_f32_16x16x32_bf16 v[42:45], v[192:195], v[208:211], v[42:45]
	v_mfma_f32_16x16x32_bf16 v[30:33], v[174:177], v[216:219], v[30:33]
	v_mfma_f32_16x16x32_bf16 v[26:29], v[192:195], v[216:219], v[26:29]
	v_mfma_f32_16x16x32_bf16 v[14:17], v[174:177], v[224:227], v[14:17]
	v_mfma_f32_16x16x32_bf16 v[10:13], v[192:195], v[224:227], v[10:13]
	v_mfma_f32_16x16x32_bf16 v[62:65], v[178:181], v[204:207], v[62:65]
	v_mfma_f32_16x16x32_bf16 v[58:61], v[196:199], v[204:207], v[58:61]
	v_mfma_f32_16x16x32_bf16 v[46:49], v[178:181], v[212:215], v[46:49]
	v_mfma_f32_16x16x32_bf16 v[42:45], v[196:199], v[212:215], v[42:45]
	v_mfma_f32_16x16x32_bf16 v[30:33], v[178:181], v[220:223], v[30:33]
	v_mfma_f32_16x16x32_bf16 v[26:29], v[196:199], v[220:223], v[26:29]
	v_mfma_f32_16x16x32_bf16 v[14:17], v[178:181], v[228:231], v[14:17]
	v_mfma_f32_16x16x32_bf16 v[10:13], v[196:199], v[228:231], v[10:13]
	s_setprio 0
	s_barrier
	s_add_i32 s54, s54, 2
	s_add_u32 s26, s26, 0x100
	s_addc_u32 s27, s27, 0
	s_add_u32 s52, s52, 0x100
	s_addc_u32 s53, s53, 0
	s_cmp_gt_u32 s54, 61
	s_cbranch_scc0 .LBB0_1539
	s_and_b64 vcc, exec, s[10:11]
	s_cbranch_vccz .LBB0_1542
	s_barrier
.LBB0_1542:
	v_lshl_add_u32 v142, s18, 8, v153
	v_ashrrev_i32_e32 v143, 31, v142
	v_lshl_add_u64 v[146:147], v[142:143], 2, s[4:5]
	v_lshl_or_b32 v144, s16, 7, v158
	v_ashrrev_i32_e32 v145, 31, v144
	v_mov_b32_e32 v254, 1.0
	v_lshl_add_u64 v[144:145], v[144:145], 1, s[6:7]
	s_andn2_b64 vcc, exec, s[20:21]
	v_mad_i64_i32 v[146:147], s[2:3], v142, s50, v[144:145]
	s_waitcnt vmcnt(7)
	v_fmamk_f32 v251, v241, 0x39800000, v161
	v_rsq_f32_e32 v251, v251
	v_pk_mul_f32 v[126:127], v[118:119], v[126:127]
	v_pk_mul_f32 v[128:129], v[120:121], v[128:129]
	v_pk_mul_f32 v[122:123], v[114:115], v[122:123]
	v_pk_mul_f32 v[124:125], v[116:117], v[124:125]
	v_mul_f32_e32 v250, 0xbfb8aa3b, v251
	v_mul_f32_e32 v252, v251, v251
	v_pk_mul_f32 v[118:119], v[118:119], v[250:251] op_sel_hi:[1,0]
	v_pk_mul_f32 v[120:121], v[120:121], v[250:251] op_sel_hi:[1,0]
	v_pk_mul_f32 v[114:115], v[114:115], v[250:251] op_sel_hi:[1,0]
	v_pk_mul_f32 v[116:117], v[116:117], v[250:251] op_sel_hi:[1,0]
	v_exp_f32_e32 v118, v118
	v_exp_f32_e32 v119, v119
	v_exp_f32_e32 v120, v120
	v_exp_f32_e32 v121, v121
	v_exp_f32_e32 v114, v114
	v_exp_f32_e32 v115, v115
	v_exp_f32_e32 v116, v116
	v_exp_f32_e32 v117, v117
	v_pk_add_f32 v[118:119], v[118:119], v[254:255] op_sel_hi:[1,0]
	v_pk_add_f32 v[120:121], v[120:121], v[254:255] op_sel_hi:[1,0]
	v_pk_add_f32 v[114:115], v[114:115], v[254:255] op_sel_hi:[1,0]
	v_pk_add_f32 v[116:117], v[116:117], v[254:255] op_sel_hi:[1,0]
	v_rcp_f32_e32 v118, v118
	v_rcp_f32_e32 v119, v119
	v_rcp_f32_e32 v120, v120
	v_rcp_f32_e32 v121, v121
	v_rcp_f32_e32 v114, v114
	v_rcp_f32_e32 v115, v115
	v_rcp_f32_e32 v116, v116
	v_rcp_f32_e32 v117, v117
	v_pk_mul_f32 v[118:119], v[118:119], v[252:253] op_sel_hi:[1,0]
	v_pk_mul_f32 v[120:121], v[120:121], v[252:253] op_sel_hi:[1,0]
	v_pk_mul_f32 v[114:115], v[114:115], v[252:253] op_sel_hi:[1,0]
	v_pk_mul_f32 v[116:117], v[116:117], v[252:253] op_sel_hi:[1,0]
	v_pk_mul_f32 v[118:119], v[126:127], v[118:119]
	v_pk_mul_f32 v[120:121], v[128:129], v[120:121]
	v_pk_mul_f32 v[114:115], v[122:123], v[114:115]
	v_pk_mul_f32 v[116:117], v[124:125], v[116:117]
	v_cvt_pk_bf16_f32 v122, v118, v119
	v_cvt_pk_bf16_f32 v123, v120, v121
	v_cvt_pk_bf16_f32 v124, v114, v115
	v_cvt_pk_bf16_f32 v125, v116, v117
	global_store_dwordx4 v[146:147], v[122:125], off
	v_add_u32_e32 v253, 16, v142
	v_mad_i64_i32 v[146:147], s[2:3], v253, s50, v[144:145]
	s_waitcnt vmcnt(6)
	v_fmamk_f32 v251, v242, 0x39800000, v161
	v_rsq_f32_e32 v251, v251
	v_pk_mul_f32 v[110:111], v[102:103], v[110:111]
	v_pk_mul_f32 v[112:113], v[104:105], v[112:113]
	v_pk_mul_f32 v[106:107], v[98:99], v[106:107]
	v_pk_mul_f32 v[108:109], v[100:101], v[108:109]
	v_mul_f32_e32 v250, 0xbfb8aa3b, v251
	v_mul_f32_e32 v252, v251, v251
	v_pk_mul_f32 v[102:103], v[102:103], v[250:251] op_sel_hi:[1,0]
	v_pk_mul_f32 v[104:105], v[104:105], v[250:251] op_sel_hi:[1,0]
	v_pk_mul_f32 v[98:99], v[98:99], v[250:251] op_sel_hi:[1,0]
	v_pk_mul_f32 v[100:101], v[100:101], v[250:251] op_sel_hi:[1,0]
	v_exp_f32_e32 v102, v102
	v_exp_f32_e32 v103, v103
	v_exp_f32_e32 v104, v104
	v_exp_f32_e32 v105, v105
	v_exp_f32_e32 v98, v98
	v_exp_f32_e32 v99, v99
	v_exp_f32_e32 v100, v100
	v_exp_f32_e32 v101, v101
	v_pk_add_f32 v[102:103], v[102:103], v[254:255] op_sel_hi:[1,0]
	v_pk_add_f32 v[104:105], v[104:105], v[254:255] op_sel_hi:[1,0]
	v_pk_add_f32 v[98:99], v[98:99], v[254:255] op_sel_hi:[1,0]
	v_pk_add_f32 v[100:101], v[100:101], v[254:255] op_sel_hi:[1,0]
	v_rcp_f32_e32 v102, v102
	v_rcp_f32_e32 v103, v103
	v_rcp_f32_e32 v104, v104
	v_rcp_f32_e32 v105, v105
	v_rcp_f32_e32 v98, v98
	v_rcp_f32_e32 v99, v99
	v_rcp_f32_e32 v100, v100
	v_rcp_f32_e32 v101, v101
	v_pk_mul_f32 v[102:103], v[102:103], v[252:253] op_sel_hi:[1,0]
	v_pk_mul_f32 v[104:105], v[104:105], v[252:253] op_sel_hi:[1,0]
	v_pk_mul_f32 v[98:99], v[98:99], v[252:253] op_sel_hi:[1,0]
	v_pk_mul_f32 v[100:101], v[100:101], v[252:253] op_sel_hi:[1,0]
	v_pk_mul_f32 v[102:103], v[110:111], v[102:103]
	v_pk_mul_f32 v[104:105], v[112:113], v[104:105]
	v_pk_mul_f32 v[98:99], v[106:107], v[98:99]
	v_pk_mul_f32 v[100:101], v[108:109], v[100:101]
	v_cvt_pk_bf16_f32 v106, v102, v103
	v_cvt_pk_bf16_f32 v107, v104, v105
	v_cvt_pk_bf16_f32 v108, v98, v99
	v_cvt_pk_bf16_f32 v109, v100, v101
	global_store_dwordx4 v[146:147], v[106:109], off
	v_add_u32_e32 v253, 32, v142
	v_mad_i64_i32 v[146:147], s[2:3], v253, s50, v[144:145]
	s_waitcnt vmcnt(5)
	v_fmamk_f32 v251, v243, 0x39800000, v161
	v_rsq_f32_e32 v251, v251
	v_pk_mul_f32 v[94:95], v[86:87], v[94:95]
	v_pk_mul_f32 v[96:97], v[88:89], v[96:97]
	v_pk_mul_f32 v[90:91], v[82:83], v[90:91]
	v_pk_mul_f32 v[92:93], v[84:85], v[92:93]
	v_mul_f32_e32 v250, 0xbfb8aa3b, v251
	v_mul_f32_e32 v252, v251, v251
	v_pk_mul_f32 v[86:87], v[86:87], v[250:251] op_sel_hi:[1,0]
	v_pk_mul_f32 v[88:89], v[88:89], v[250:251] op_sel_hi:[1,0]
	v_pk_mul_f32 v[82:83], v[82:83], v[250:251] op_sel_hi:[1,0]
	v_pk_mul_f32 v[84:85], v[84:85], v[250:251] op_sel_hi:[1,0]
	v_exp_f32_e32 v86, v86
	v_exp_f32_e32 v87, v87
	v_exp_f32_e32 v88, v88
	v_exp_f32_e32 v89, v89
	v_exp_f32_e32 v82, v82
	v_exp_f32_e32 v83, v83
	v_exp_f32_e32 v84, v84
	v_exp_f32_e32 v85, v85
	v_pk_add_f32 v[86:87], v[86:87], v[254:255] op_sel_hi:[1,0]
	v_pk_add_f32 v[88:89], v[88:89], v[254:255] op_sel_hi:[1,0]
	v_pk_add_f32 v[82:83], v[82:83], v[254:255] op_sel_hi:[1,0]
	v_pk_add_f32 v[84:85], v[84:85], v[254:255] op_sel_hi:[1,0]
	v_rcp_f32_e32 v86, v86
	v_rcp_f32_e32 v87, v87
	v_rcp_f32_e32 v88, v88
	v_rcp_f32_e32 v89, v89
	v_rcp_f32_e32 v82, v82
	v_rcp_f32_e32 v83, v83
	v_rcp_f32_e32 v84, v84
	v_rcp_f32_e32 v85, v85
	v_pk_mul_f32 v[86:87], v[86:87], v[252:253] op_sel_hi:[1,0]
	v_pk_mul_f32 v[88:89], v[88:89], v[252:253] op_sel_hi:[1,0]
	v_pk_mul_f32 v[82:83], v[82:83], v[252:253] op_sel_hi:[1,0]
	v_pk_mul_f32 v[84:85], v[84:85], v[252:253] op_sel_hi:[1,0]
	v_pk_mul_f32 v[86:87], v[94:95], v[86:87]
	v_pk_mul_f32 v[88:89], v[96:97], v[88:89]
	v_pk_mul_f32 v[82:83], v[90:91], v[82:83]
	v_pk_mul_f32 v[84:85], v[92:93], v[84:85]
	v_cvt_pk_bf16_f32 v90, v86, v87
	v_cvt_pk_bf16_f32 v91, v88, v89
	v_cvt_pk_bf16_f32 v92, v82, v83
	v_cvt_pk_bf16_f32 v93, v84, v85
	global_store_dwordx4 v[146:147], v[90:93], off
	v_add_u32_e32 v253, 48, v142
	v_mad_i64_i32 v[146:147], s[2:3], v253, s50, v[144:145]
	s_waitcnt vmcnt(4)
	v_fmamk_f32 v251, v244, 0x39800000, v161
	v_rsq_f32_e32 v251, v251
	v_pk_mul_f32 v[78:79], v[70:71], v[78:79]
	v_pk_mul_f32 v[80:81], v[72:73], v[80:81]
	v_pk_mul_f32 v[74:75], v[66:67], v[74:75]
	v_pk_mul_f32 v[76:77], v[68:69], v[76:77]
	v_mul_f32_e32 v250, 0xbfb8aa3b, v251
	v_mul_f32_e32 v252, v251, v251
	v_pk_mul_f32 v[70:71], v[70:71], v[250:251] op_sel_hi:[1,0]
	v_pk_mul_f32 v[72:73], v[72:73], v[250:251] op_sel_hi:[1,0]
	v_pk_mul_f32 v[66:67], v[66:67], v[250:251] op_sel_hi:[1,0]
	v_pk_mul_f32 v[68:69], v[68:69], v[250:251] op_sel_hi:[1,0]
	v_exp_f32_e32 v70, v70
	v_exp_f32_e32 v71, v71
	v_exp_f32_e32 v72, v72
	v_exp_f32_e32 v73, v73
	v_exp_f32_e32 v66, v66
	v_exp_f32_e32 v67, v67
	v_exp_f32_e32 v68, v68
	v_exp_f32_e32 v69, v69
	v_pk_add_f32 v[70:71], v[70:71], v[254:255] op_sel_hi:[1,0]
	v_pk_add_f32 v[72:73], v[72:73], v[254:255] op_sel_hi:[1,0]
	v_pk_add_f32 v[66:67], v[66:67], v[254:255] op_sel_hi:[1,0]
	v_pk_add_f32 v[68:69], v[68:69], v[254:255] op_sel_hi:[1,0]
	v_rcp_f32_e32 v70, v70
	v_rcp_f32_e32 v71, v71
	v_rcp_f32_e32 v72, v72
	v_rcp_f32_e32 v73, v73
	v_rcp_f32_e32 v66, v66
	v_rcp_f32_e32 v67, v67
	v_rcp_f32_e32 v68, v68
	v_rcp_f32_e32 v69, v69
	v_pk_mul_f32 v[70:71], v[70:71], v[252:253] op_sel_hi:[1,0]
	v_pk_mul_f32 v[72:73], v[72:73], v[252:253] op_sel_hi:[1,0]
	v_pk_mul_f32 v[66:67], v[66:67], v[252:253] op_sel_hi:[1,0]
	v_pk_mul_f32 v[68:69], v[68:69], v[252:253] op_sel_hi:[1,0]
	v_pk_mul_f32 v[70:71], v[78:79], v[70:71]
	v_pk_mul_f32 v[72:73], v[80:81], v[72:73]
	v_pk_mul_f32 v[66:67], v[74:75], v[66:67]
	v_pk_mul_f32 v[68:69], v[76:77], v[68:69]
	v_cvt_pk_bf16_f32 v74, v70, v71
	v_cvt_pk_bf16_f32 v75, v72, v73
	v_cvt_pk_bf16_f32 v76, v66, v67
	v_cvt_pk_bf16_f32 v77, v68, v69
	global_store_dwordx4 v[146:147], v[74:77], off
	v_add_u32_e32 v253, 128, v142
	v_mad_i64_i32 v[146:147], s[2:3], v253, s50, v[144:145]
	s_waitcnt vmcnt(3)
	v_fmamk_f32 v251, v245, 0x39800000, v161
	v_rsq_f32_e32 v251, v251
	v_pk_mul_f32 v[62:63], v[54:55], v[62:63]
	v_pk_mul_f32 v[64:65], v[56:57], v[64:65]
	v_pk_mul_f32 v[58:59], v[50:51], v[58:59]
	v_pk_mul_f32 v[60:61], v[52:53], v[60:61]
	v_mul_f32_e32 v250, 0xbfb8aa3b, v251
	v_mul_f32_e32 v252, v251, v251
	v_pk_mul_f32 v[54:55], v[54:55], v[250:251] op_sel_hi:[1,0]
	v_pk_mul_f32 v[56:57], v[56:57], v[250:251] op_sel_hi:[1,0]
	v_pk_mul_f32 v[50:51], v[50:51], v[250:251] op_sel_hi:[1,0]
	v_pk_mul_f32 v[52:53], v[52:53], v[250:251] op_sel_hi:[1,0]
	v_exp_f32_e32 v54, v54
	v_exp_f32_e32 v55, v55
	v_exp_f32_e32 v56, v56
	v_exp_f32_e32 v57, v57
	v_exp_f32_e32 v50, v50
	v_exp_f32_e32 v51, v51
	v_exp_f32_e32 v52, v52
	v_exp_f32_e32 v53, v53
	v_pk_add_f32 v[54:55], v[54:55], v[254:255] op_sel_hi:[1,0]
	v_pk_add_f32 v[56:57], v[56:57], v[254:255] op_sel_hi:[1,0]
	v_pk_add_f32 v[50:51], v[50:51], v[254:255] op_sel_hi:[1,0]
	v_pk_add_f32 v[52:53], v[52:53], v[254:255] op_sel_hi:[1,0]
	v_rcp_f32_e32 v54, v54
	v_rcp_f32_e32 v55, v55
	v_rcp_f32_e32 v56, v56
	v_rcp_f32_e32 v57, v57
	v_rcp_f32_e32 v50, v50
	v_rcp_f32_e32 v51, v51
	v_rcp_f32_e32 v52, v52
	v_rcp_f32_e32 v53, v53
	v_pk_mul_f32 v[54:55], v[54:55], v[252:253] op_sel_hi:[1,0]
	v_pk_mul_f32 v[56:57], v[56:57], v[252:253] op_sel_hi:[1,0]
	v_pk_mul_f32 v[50:51], v[50:51], v[252:253] op_sel_hi:[1,0]
	v_pk_mul_f32 v[52:53], v[52:53], v[252:253] op_sel_hi:[1,0]
	v_pk_mul_f32 v[54:55], v[62:63], v[54:55]
	v_pk_mul_f32 v[56:57], v[64:65], v[56:57]
	v_pk_mul_f32 v[50:51], v[58:59], v[50:51]
	v_pk_mul_f32 v[52:53], v[60:61], v[52:53]
	v_cvt_pk_bf16_f32 v58, v54, v55
	v_cvt_pk_bf16_f32 v59, v56, v57
	v_cvt_pk_bf16_f32 v60, v50, v51
	v_cvt_pk_bf16_f32 v61, v52, v53
	global_store_dwordx4 v[146:147], v[58:61], off
	v_add_u32_e32 v253, 144, v142
	v_mad_i64_i32 v[146:147], s[2:3], v253, s50, v[144:145]
	s_waitcnt vmcnt(2)
	v_fmamk_f32 v251, v246, 0x39800000, v161
	v_rsq_f32_e32 v251, v251
	v_pk_mul_f32 v[46:47], v[38:39], v[46:47]
	v_pk_mul_f32 v[48:49], v[40:41], v[48:49]
	v_pk_mul_f32 v[42:43], v[34:35], v[42:43]
	v_pk_mul_f32 v[44:45], v[36:37], v[44:45]
	v_mul_f32_e32 v250, 0xbfb8aa3b, v251
	v_mul_f32_e32 v252, v251, v251
	v_pk_mul_f32 v[38:39], v[38:39], v[250:251] op_sel_hi:[1,0]
	v_pk_mul_f32 v[40:41], v[40:41], v[250:251] op_sel_hi:[1,0]
	v_pk_mul_f32 v[34:35], v[34:35], v[250:251] op_sel_hi:[1,0]
	v_pk_mul_f32 v[36:37], v[36:37], v[250:251] op_sel_hi:[1,0]
	v_exp_f32_e32 v38, v38
	v_exp_f32_e32 v39, v39
	v_exp_f32_e32 v40, v40
	v_exp_f32_e32 v41, v41
	v_exp_f32_e32 v34, v34
	v_exp_f32_e32 v35, v35
	v_exp_f32_e32 v36, v36
	v_exp_f32_e32 v37, v37
	v_pk_add_f32 v[38:39], v[38:39], v[254:255] op_sel_hi:[1,0]
	v_pk_add_f32 v[40:41], v[40:41], v[254:255] op_sel_hi:[1,0]
	v_pk_add_f32 v[34:35], v[34:35], v[254:255] op_sel_hi:[1,0]
	v_pk_add_f32 v[36:37], v[36:37], v[254:255] op_sel_hi:[1,0]
	v_rcp_f32_e32 v38, v38
	v_rcp_f32_e32 v39, v39
	v_rcp_f32_e32 v40, v40
	v_rcp_f32_e32 v41, v41
	v_rcp_f32_e32 v34, v34
	v_rcp_f32_e32 v35, v35
	v_rcp_f32_e32 v36, v36
	v_rcp_f32_e32 v37, v37
	v_pk_mul_f32 v[38:39], v[38:39], v[252:253] op_sel_hi:[1,0]
	v_pk_mul_f32 v[40:41], v[40:41], v[252:253] op_sel_hi:[1,0]
	v_pk_mul_f32 v[34:35], v[34:35], v[252:253] op_sel_hi:[1,0]
	v_pk_mul_f32 v[36:37], v[36:37], v[252:253] op_sel_hi:[1,0]
	v_pk_mul_f32 v[38:39], v[46:47], v[38:39]
	v_pk_mul_f32 v[40:41], v[48:49], v[40:41]
	v_pk_mul_f32 v[34:35], v[42:43], v[34:35]
	v_pk_mul_f32 v[36:37], v[44:45], v[36:37]
	v_cvt_pk_bf16_f32 v42, v38, v39
	v_cvt_pk_bf16_f32 v43, v40, v41
	v_cvt_pk_bf16_f32 v44, v34, v35
	v_cvt_pk_bf16_f32 v45, v36, v37
	global_store_dwordx4 v[146:147], v[42:45], off
	v_add_u32_e32 v253, 160, v142
	v_mad_i64_i32 v[146:147], s[2:3], v253, s50, v[144:145]
	s_waitcnt vmcnt(1)
	v_fmamk_f32 v251, v247, 0x39800000, v161
	v_rsq_f32_e32 v251, v251
	v_pk_mul_f32 v[30:31], v[22:23], v[30:31]
	v_pk_mul_f32 v[32:33], v[24:25], v[32:33]
	v_pk_mul_f32 v[26:27], v[18:19], v[26:27]
	v_pk_mul_f32 v[28:29], v[20:21], v[28:29]
	v_mul_f32_e32 v250, 0xbfb8aa3b, v251
	v_mul_f32_e32 v252, v251, v251
	v_pk_mul_f32 v[22:23], v[22:23], v[250:251] op_sel_hi:[1,0]
	v_pk_mul_f32 v[24:25], v[24:25], v[250:251] op_sel_hi:[1,0]
	v_pk_mul_f32 v[18:19], v[18:19], v[250:251] op_sel_hi:[1,0]
	v_pk_mul_f32 v[20:21], v[20:21], v[250:251] op_sel_hi:[1,0]
	v_exp_f32_e32 v22, v22
	v_exp_f32_e32 v23, v23
	v_exp_f32_e32 v24, v24
	v_exp_f32_e32 v25, v25
	v_exp_f32_e32 v18, v18
	v_exp_f32_e32 v19, v19
	v_exp_f32_e32 v20, v20
	v_exp_f32_e32 v21, v21
	v_pk_add_f32 v[22:23], v[22:23], v[254:255] op_sel_hi:[1,0]
	v_pk_add_f32 v[24:25], v[24:25], v[254:255] op_sel_hi:[1,0]
	v_pk_add_f32 v[18:19], v[18:19], v[254:255] op_sel_hi:[1,0]
	v_pk_add_f32 v[20:21], v[20:21], v[254:255] op_sel_hi:[1,0]
	v_rcp_f32_e32 v22, v22
	v_rcp_f32_e32 v23, v23
	v_rcp_f32_e32 v24, v24
	v_rcp_f32_e32 v25, v25
	v_rcp_f32_e32 v18, v18
	v_rcp_f32_e32 v19, v19
	v_rcp_f32_e32 v20, v20
	v_rcp_f32_e32 v21, v21
	v_pk_mul_f32 v[22:23], v[22:23], v[252:253] op_sel_hi:[1,0]
	v_pk_mul_f32 v[24:25], v[24:25], v[252:253] op_sel_hi:[1,0]
	v_pk_mul_f32 v[18:19], v[18:19], v[252:253] op_sel_hi:[1,0]
	v_pk_mul_f32 v[20:21], v[20:21], v[252:253] op_sel_hi:[1,0]
	v_pk_mul_f32 v[22:23], v[30:31], v[22:23]
	v_pk_mul_f32 v[24:25], v[32:33], v[24:25]
	v_pk_mul_f32 v[18:19], v[26:27], v[18:19]
	v_pk_mul_f32 v[20:21], v[28:29], v[20:21]
	v_cvt_pk_bf16_f32 v26, v22, v23
	v_cvt_pk_bf16_f32 v27, v24, v25
	v_cvt_pk_bf16_f32 v28, v18, v19
	v_cvt_pk_bf16_f32 v29, v20, v21
	global_store_dwordx4 v[146:147], v[26:29], off
	v_add_u32_e32 v253, 176, v142
	v_mad_i64_i32 v[146:147], s[2:3], v253, s50, v[144:145]
	s_mov_b64 s[2:3], -1
	s_waitcnt vmcnt(0)
	v_fmamk_f32 v251, v248, 0x39800000, v161
	v_rsq_f32_e32 v251, v251
	v_pk_mul_f32 v[14:15], v[6:7], v[14:15]
	v_pk_mul_f32 v[16:17], v[8:9], v[16:17]
	v_pk_mul_f32 v[10:11], v[2:3], v[10:11]
	v_pk_mul_f32 v[12:13], v[4:5], v[12:13]
	v_mul_f32_e32 v250, 0xbfb8aa3b, v251
	v_mul_f32_e32 v252, v251, v251
	v_pk_mul_f32 v[6:7], v[6:7], v[250:251] op_sel_hi:[1,0]
	v_pk_mul_f32 v[8:9], v[8:9], v[250:251] op_sel_hi:[1,0]
	v_pk_mul_f32 v[2:3], v[2:3], v[250:251] op_sel_hi:[1,0]
	v_pk_mul_f32 v[4:5], v[4:5], v[250:251] op_sel_hi:[1,0]
	v_exp_f32_e32 v6, v6
	v_exp_f32_e32 v7, v7
	v_exp_f32_e32 v8, v8
	v_exp_f32_e32 v9, v9
	v_exp_f32_e32 v2, v2
	v_exp_f32_e32 v3, v3
	v_exp_f32_e32 v4, v4
	v_exp_f32_e32 v5, v5
	v_pk_add_f32 v[6:7], v[6:7], v[254:255] op_sel_hi:[1,0]
	v_pk_add_f32 v[8:9], v[8:9], v[254:255] op_sel_hi:[1,0]
	v_pk_add_f32 v[2:3], v[2:3], v[254:255] op_sel_hi:[1,0]
	v_pk_add_f32 v[4:5], v[4:5], v[254:255] op_sel_hi:[1,0]
	v_rcp_f32_e32 v6, v6
	v_rcp_f32_e32 v7, v7
	v_rcp_f32_e32 v8, v8
	v_rcp_f32_e32 v9, v9
	v_rcp_f32_e32 v2, v2
	v_rcp_f32_e32 v3, v3
	v_rcp_f32_e32 v4, v4
	v_rcp_f32_e32 v5, v5
	v_pk_mul_f32 v[6:7], v[6:7], v[252:253] op_sel_hi:[1,0]
	v_pk_mul_f32 v[8:9], v[8:9], v[252:253] op_sel_hi:[1,0]
	v_pk_mul_f32 v[2:3], v[2:3], v[252:253] op_sel_hi:[1,0]
	v_pk_mul_f32 v[4:5], v[4:5], v[252:253] op_sel_hi:[1,0]
	v_pk_mul_f32 v[6:7], v[14:15], v[6:7]
	v_pk_mul_f32 v[8:9], v[16:17], v[8:9]
	v_pk_mul_f32 v[2:3], v[10:11], v[2:3]
	v_pk_mul_f32 v[4:5], v[12:13], v[4:5]
	v_cvt_pk_bf16_f32 v10, v6, v7
	v_cvt_pk_bf16_f32 v11, v8, v9
	v_cvt_pk_bf16_f32 v12, v2, v3
	v_cvt_pk_bf16_f32 v13, v4, v5
	global_store_dwordx4 v[146:147], v[10:13], off
	s_cbranch_vccnz .LBB0_1464
	s_andn2_b64 vcc, exec, s[0:1]
	s_cbranch_vccnz .LBB0_1463
	s_barrier
	s_branch .LBB0_1463
